# speedup vs baseline: 1.0186x; 1.0186x over previous
; DEVI int otid() { int t = threadIdx.x; asm volatile("" : "+v"(t)); return t; }
; DEVI int v_st(int k, int c) { const int kk = (k & ~0xC) | ((k & 4) << 1) | ((k & 8) >> 1); return ((kk >> 3) * 4 + (c >> 5)) * 512 + ((kk & 7) * 32 + (c & 31)) * 2; }
; DEVI int v_rd_base(int lane) { return ((lane & 3) << 3) | (((lane >> 2) & 3) << 6) | (((lane >> 4) & 1) << 5) | (((lane >> 5) & 1) << 8); }
; template <bool FIX>
; DEVI void attn_item(const bfr* __restrict__ Qb, const bfr* __restrict__ Kh, const bfr* __restrict__ Vh, bfr* __restrict__ Ob, int seq, char* lds, float negBC) {
;   const int tid = otid(), wid = tid >> 6, lane = tid & 63, r32 = lane & 31, hi = lane >> 5;
;   char* V_lds = lds; char* K_lds = lds + 2 * SHM_V;
;   float* ws = (float*)(lds + 2 * SHM_V + 2 * SHM_K) + wid * 64; float* li_l = ws; float* al_l = ws + 32;
;   float m_reg = -1e30f, l_reg = 0; f32x16 o[4] = {}; bf16x8 qr[12];
;   const bfr* Qw = Qb + (long)(wid * QBLK + r32) * LDQ + hi * 8;
; #pragma unroll
;   for (int d0 = 0; d0 < 12; ++d0) qr[d0] = *reinterpret_cast<const bf16x8*>(Qw + d0 * 16);
;   const int sr = tid >> 4, sc = (tid & 15) * 8, vst0 = v_st(sr, sc), vst1 = v_st(32 + sr, sc);
;   const int kr = tid >> 3, kc = 128 + (tid & 7) * 8;
;   const int vb0 = (int)(uintptr_t)V_lds + v_rd_base(lane);
;   struct { bf16x8 vs0, vs1, ks0, ks1, ks2; } sr_[1];
;     ...
;   f32x16 pA0, pA1; float mnA, alA; bf16x8 pa0, pa1, pa2, pa3; const int NT = seq / KVBLK;
;   SLOAD(0, 0); asm volatile("s_waitcnt vmcnt(0)" ::: "memory"); SWRITE(0, 0); SLOAD(0, KVBLK); __syncthreads();
.LBB0_118:
	s_and_b64 vcc, exec, s[0:1]
	s_cbranch_vccz .LBB0_95
	v_mov_b32_e32 v184, v164
	s_movk_i32 s0, 0xffe0
	v_ashrrev_i32_e32 v0, 1, v184
	v_bfe_u32 v183, v184, 5, 1
	v_and_b32_e32 v170, 0xffffffe0, v0
	v_bfi_b32 v2, s0, v0, v184
	v_mov_b64_e32 v[0:1], s[8:9]
	s_movk_i32 s2, 0x1800
	v_mad_i64_i32 v[0:1], s[0:1], v2, s2, v[0:1]
	v_lshlrev_b32_e32 v166, 4, v183
	v_lshl_add_u64 v[0:1], v[0:1], 0, v[166:167]
	global_load_dwordx4 v[140:143], v[0:1], off
	global_load_dwordx4 v[136:139], v[0:1], off offset:32
	global_load_dwordx4 v[132:135], v[0:1], off offset:64
	global_load_dwordx4 v[128:131], v[0:1], off offset:96
	global_load_dwordx4 v[124:127], v[0:1], off offset:128
	global_load_dwordx4 v[120:123], v[0:1], off offset:160
	global_load_dwordx4 v[116:119], v[0:1], off offset:192
	global_load_dwordx4 v[112:115], v[0:1], off offset:224
	global_load_dwordx4 v[108:111], v[0:1], off offset:256
	global_load_dwordx4 v[104:107], v[0:1], off offset:288
	global_load_dwordx4 v[100:103], v[0:1], off offset:320
	global_load_dwordx4 v[96:99], v[0:1], off offset:352
	v_ashrrev_i32_e32 v0, 4, v184
	v_and_b32_e32 v2, 0xfffff0, v0
	v_lshlrev_b32_e32 v3, 1, v0
	v_lshlrev_b32_e32 v28, 3, v184
	v_and_or_b32 v2, v3, 8, v2
	v_lshrrev_b32_e32 v2, 1, v2
	v_bfe_u32 v4, v28, 5, 2
	v_or_b32_e32 v2, v2, v4
	v_lshrrev_b32_e32 v3, 1, v0
	v_lshlrev_b32_e32 v5, 9, v2
	v_and_b32_e32 v2, 3, v0
	v_and_b32_e32 v1, 0x78, v28
	v_and_or_b32 v2, v3, 4, v2
	v_lshlrev_b32_e32 v3, 6, v2
	v_lshlrev_b32_e32 v2, 1, v1
	v_and_b32_e32 v1, 48, v2
	v_add_u32_e32 v20, 32, v0
	v_or3_b32 v185, v5, v3, v1
	v_and_b32_e32 v5, 0xfffff0, v20
	v_lshlrev_b32_e32 v6, 1, v20
	v_and_or_b32 v5, v6, 8, v5
	v_lshrrev_b32_e32 v5, 1, v5
	v_or_b32_e32 v4, v5, v4
	v_lshlrev_b32_e32 v4, 9, v4
	v_or3_b32 v186, v4, v3, v1
	v_ashrrev_i32_e32 v1, 31, v0
	v_lshlrev_b64 v[6:7], 12, v[0:1]
	v_lshl_add_u64 v[6:7], s[82:83], 0, v[6:7]
	v_mov_b32_e32 v3, v167
	v_lshl_add_u64 v[6:7], v[6:7], 0, v[2:3]
	v_ashrrev_i32_e32 v21, 31, v20
	global_load_dwordx4 v[8:11], v[6:7], off
	v_lshlrev_b64 v[6:7], 12, v[20:21]
	v_lshl_add_u64 v[6:7], s[82:83], 0, v[6:7]
	v_lshl_add_u64 v[6:7], v[6:7], 0, v[2:3]
	v_ashrrev_i32_e32 v29, 3, v184
	v_lshlrev_b32_e32 v30, 4, v184
	global_load_dwordx4 v[12:15], v[6:7], off
	v_mov_b64_e32 v[6:7], s[34:35]
	v_and_b32_e32 v4, 0x70, v30
	v_mad_i64_i32 v[16:17], s[0:1], v0, s2, v[6:7]
	v_mad_i64_i32 v[24:25], s[0:1], v29, s2, v[6:7]
	v_mov_b32_e32 v5, v167
	v_lshl_add_u64 v[16:17], v[16:17], 0, v[2:3]
	v_mad_i64_i32 v[20:21], s[0:1], v20, s2, v[6:7]
	v_lshl_add_u64 v[24:25], v[24:25], 0, v[4:5]
	global_load_dwordx4 v[16:19], v[16:17], off
	v_lshl_add_u64 v[20:21], v[20:21], 0, v[2:3]
	global_load_dwordx4 v[24:27], v[24:25], off offset:256
	s_movk_i32 s4, 0x190
	global_load_dwordx4 v[20:23], v[20:21], off
	s_waitcnt vmcnt(0)
	v_mad_u64_u32 v[172:173], s[0:1], v0, s4, v[2:3]
	v_add_u32_e32 v1, 64, v29
	v_and_b32_e32 v182, 31, v184
	v_mov_b32_e32 v173, 0
	v_and_b32_e32 v171, 63, v184
	v_lshl_add_u64 v[174:175], s[82:83], 0, v[2:3]
	v_lshl_add_u64 v[176:177], s[34:35], 0, v[2:3]
	v_lshl_add_u64 v[178:179], s[34:35], 0, v[4:5]
	v_mul_u32_u24_e32 v189, 0x190, v182
	v_add_u32_e32 v190, 0x80, v29
	v_add_u32_e32 v180, 0xa0, v0
	v_mov_b32_e32 v31, v173
	v_mov_b32_e32 v32, 0
	v_mov_b32_e32 v33, v173
	v_mov_b32_e32 v34, v173
	v_mov_b32_e32 v35, v173
	v_mov_b32_e32 v36, v173
	v_mov_b32_e32 v37, v173
	v_mov_b32_e32 v38, v173
	v_mov_b32_e32 v39, v173
	v_mov_b32_e32 v40, v173
	v_mov_b32_e32 v41, v173
	v_mov_b32_e32 v42, v173
	v_mov_b32_e32 v43, v173
	v_mov_b32_e32 v44, v173
	v_mov_b32_e32 v45, v173
	v_mov_b32_e32 v46, v173
	v_mov_b32_e32 v47, v173
	v_mov_b32_e32 v48, 0
	v_mov_b32_e32 v49, v173
	v_mov_b32_e32 v50, v173
	v_mov_b32_e32 v51, v173
	v_mov_b32_e32 v52, v173
	v_mov_b32_e32 v53, v173
	v_mov_b32_e32 v54, v173
	s_waitcnt vmcnt(0) lgkmcnt(0)
	ds_write_b128 v185, v[8:11]
	ds_write_b128 v186, v[12:15]
	v_mad_u64_u32 v[8:9], s[0:1], v29, s4, v[4:5]
	ds_write_b128 v172, v[16:19] offset:32768
	ds_write_b128 v172, v[20:23] offset:45568
	v_add_u32_e32 v188, 0x100, v8
	ds_write_b128 v8, v[24:27] offset:33024
	v_add_u32_e32 v8, 64, v0
	v_ashrrev_i32_e32 v9, 31, v8
	v_lshlrev_b64 v[10:11], 12, v[8:9]
	v_lshl_add_u64 v[10:11], s[82:83], 0, v[10:11]
	v_mad_i64_i32 v[8:9], s[0:1], v8, s2, v[6:7]
	v_lshl_add_u64 v[10:11], v[10:11], 0, v[2:3]
	v_lshl_add_u64 v[8:9], v[8:9], 0, v[2:3]
	global_load_dwordx4 v[144:147], v[10:11], off
	global_load_dwordx4 v[152:155], v[8:9], off
	v_add_u32_e32 v10, 0x60, v0
	v_ashrrev_i32_e32 v11, 31, v10
	v_lshlrev_b64 v[12:13], 12, v[10:11]
	v_lshl_add_u64 v[12:13], s[82:83], 0, v[12:13]
	v_mad_i64_i32 v[8:9], s[0:1], v10, s2, v[6:7]
	v_mad_i64_i32 v[6:7], s[0:1], v1, s2, v[6:7]
	v_lshl_add_u64 v[12:13], v[12:13], 0, v[2:3]
	v_lshl_add_u64 v[8:9], v[8:9], 0, v[2:3]
	v_lshl_add_u64 v[6:7], v[6:7], 0, v[4:5]
	global_load_dwordx4 v[148:151], v[12:13], off
	global_load_dwordx4 v[156:159], v[8:9], off
	global_load_dwordx4 v[160:163], v[6:7], off offset:256
	v_lshlrev_b32_e32 v1, 1, v184
	v_and_b32_e32 v1, 32, v1
	s_movk_i32 s0, 0x118
	v_and_or_b32 v1, v28, s0, v1
	v_and_or_b32 v187, v30, s77, v1
	s_add_i32 s0, s64, -1
	s_mov_b32 s1, 0
	v_mov_b32_e32 v0, 0
	v_mov_b32_e32 v1, v173
	v_mov_b32_e32 v2, v173
	v_mov_b32_e32 v3, v173
	v_mov_b32_e32 v4, v173
	v_mov_b32_e32 v5, v173
	v_mov_b32_e32 v6, v173
	v_mov_b32_e32 v7, v173
	v_mov_b32_e32 v8, v173
	v_mov_b32_e32 v9, v173
	v_mov_b32_e32 v10, v173
	v_mov_b32_e32 v11, v173
	v_mov_b32_e32 v12, v173
	v_mov_b32_e32 v13, v173
	v_mov_b32_e32 v14, v173
	v_mov_b32_e32 v15, v173
	v_mov_b32_e32 v16, 0
	v_mov_b32_e32 v17, v173
	v_mov_b32_e32 v18, v173
	v_mov_b32_e32 v19, v173
	v_mov_b32_e32 v20, v173
	v_mov_b32_e32 v21, v173
	v_mov_b32_e32 v22, v173
	v_mov_b32_e32 v23, v173
	v_mov_b32_e32 v24, v173
	v_mov_b32_e32 v25, v173
	v_mov_b32_e32 v26, v173
	v_mov_b32_e32 v27, v173
	v_mov_b32_e32 v28, v173
	v_mov_b32_e32 v29, v173
	v_mov_b32_e32 v30, v173
	v_mov_b32_e32 v55, v173
	v_mov_b32_e32 v56, v173
	v_mov_b32_e32 v57, v173
	v_mov_b32_e32 v58, v173
	v_mov_b32_e32 v59, v173
	v_mov_b32_e32 v60, v173
	v_mov_b32_e32 v61, v173
	v_mov_b32_e32 v62, v173
	v_mov_b32_e32 v63, v173
	s_waitcnt lgkmcnt(0)
	s_barrier
	s_mov_b32 s100, 0x4000
	s_branch .LBB0_121
; #define SCHEDB() __builtin_amdgcn_sched_barrier(0)
; #define RESC(a) do { if (__any((a) < 1.f)) { if (hi == 0) al_l[r32] = (a); asm volatile("s_waitcnt lgkmcnt(0)" ::: "memory"); \
;     _Pragma("unroll") for (int d = 0; d < 4; ++d) _Pragma("unroll") for (int r = 0; r < 16; ++r) o[d][r] *= al_l[crow(r, hi)]; } } while (0)
; DEVI void qkt(f32x16& p0, f32x16& p1, const char* Ks, const bf16x8* qr, int r32, int hi) {
;   p0 = f32x16{}; p1 = f32x16{};
; #pragma unroll
;   for (int d0 = 0; d0 < 12; ++d0) { int cb = (d0 * 16 + hi * 8) * 2;
;     bf16x8 b0 = *reinterpret_cast<const bf16x8*>(Ks + KSWZ(r32, cb));
;     bf16x8 b1 = *reinterpret_cast<const bf16x8*>(Ks + KSWZ(32 + r32, cb));
;     p0 = __builtin_amdgcn_mfma_f32_32x32x16_bf16(b0, qr[d0], p0, 0, 0, 0);
;     p1 = __builtin_amdgcn_mfma_f32_32x32x16_bf16(b1, qr[d0], p1, 0, 0, 0); }
; }
; template <bool FIX>
; DEVI void attn_item(const bfr* __restrict__ Qb, const bfr* __restrict__ Kh, const bfr* __restrict__ Vh, bfr* __restrict__ Ob, int seq, char* lds, float negBC) {
;     ...
;   for (int j = 0; j < NT; ++j) {
;     const int buf = j & 1;
;     SCHEDB(); qkt(pA0, pA1, K_lds + buf * SHM_K, qr, r32, hi);
;     if (j + 1 < NT) { SWRITE(buf ^ 1, 0); if (j + 2 < NT) SLOAD(0, (j + 2) * KVBLK); }
;     if constexpr (FIX) { partialSM_fix(pA0, pA1); alA = 1.f; }
;     else { partialSM(pA0, pA1, m_reg, mnA, alA); RESC(alA); }
;     finishSM(pA0, pA1, alA, l_reg, pa0, pa1, pa2, pa3); SCHEDB();
;     __builtin_amdgcn_s_setprio(1); pv_d0(o, vb0 + buf * SHM_V, pa0, pa1, pa2, pa3); __builtin_amdgcn_s_setprio(0);
.LBB0_121:
	s_and_b32 s2, s1, 1
	s_mul_i32 s4, s2, 0x6400
	v_add3_u32 v191, s4, v189, v166
	s_xor_b32 s4, s2, 1
	s_mulk_i32 s4, 0x6400
	s_cmp_eq_u32 s100, 0x4000
	s_cselect_b32 s101, 0x15000, 0
	s_cmp_eq_u32 s100, 0
	s_cselect_b32 s101, 0x4000, s101
	v_add_u32_e32 v194, s101, v187
	ds_read_b128 v[196:199], v191 offset:32768
	ds_read_b128 v[200:203], v191 offset:32800
	ds_read_b128 v[204:207], v191 offset:32832
	ds_read_b128 v[224:227], v191 offset:32864
	ds_read_b128 v[228:231], v191 offset:32896
	ds_read_b128 v[232:235], v191 offset:32928
	ds_read_b128 v[236:239], v191 offset:32960
	ds_read_b128 v[240:243], v191 offset:32992
	v_cvt_pk_bf16_f32 v208, v80, v81
	v_cvt_pk_bf16_f32 v209, v82, v83
	v_cvt_pk_bf16_f32 v210, v84, v85
	v_cvt_pk_bf16_f32 v211, v86, v87
	v_cvt_pk_bf16_f32 v212, v88, v89
	v_cvt_pk_bf16_f32 v213, v90, v91
	v_cvt_pk_bf16_f32 v214, v92, v93
	v_cvt_pk_bf16_f32 v215, v94, v95
	v_cvt_pk_bf16_f32 v216, v64, v65
	v_cvt_pk_bf16_f32 v217, v66, v67
	v_cvt_pk_bf16_f32 v218, v68, v69
	v_cvt_pk_bf16_f32 v219, v70, v71
	v_cvt_pk_bf16_f32 v220, v72, v73
	v_cvt_pk_bf16_f32 v221, v74, v75
	v_cvt_pk_bf16_f32 v222, v76, v77
	v_cvt_pk_bf16_f32 v223, v78, v79
	s_nop 1
	v_permlane32_swap_b32_e32 v208, v210
	v_permlane32_swap_b32_e32 v209, v211
	v_permlane32_swap_b32_e32 v212, v214
	v_permlane32_swap_b32_e32 v213, v215
	v_permlane32_swap_b32_e32 v216, v218
	v_permlane32_swap_b32_e32 v217, v219
	v_permlane32_swap_b32_e32 v220, v222
	v_permlane32_swap_b32_e32 v221, v223
	s_waitcnt lgkmcnt(7)
	v_mfma_f32_32x32x16_bf16 v[80:95], v[196:199], v[140:143], 0
	ds_read_b128 v[244:247], v191 offset:33024
	s_waitcnt lgkmcnt(7)
	v_mfma_f32_32x32x16_bf16 v[80:95], v[200:203], v[136:139], v[80:95]
	ds_read_b128 v[248:251], v191 offset:33056
	v_add_u32_e32 v181, s100, v185
	s_waitcnt vmcnt(0)
	ds_write_b128 v181, v[144:147]
	s_waitcnt lgkmcnt(8)
	v_mfma_f32_32x32x16_bf16 v[80:95], v[204:207], v[132:135], v[80:95]
	ds_read_b128 v[196:199], v191 offset:33088
	v_add_u32_e32 v181, s100, v186
	ds_write_b128 v181, v[148:151]
	s_waitcnt lgkmcnt(9)
	v_mfma_f32_32x32x16_bf16 v[80:95], v[224:227], v[128:131], v[80:95]
	ds_read_b128 v[200:203], v191 offset:33120
	v_add_u32_e32 v181, s4, v172
	ds_write_b128 v181, v[152:155] offset:32768
	s_waitcnt lgkmcnt(10)
	v_mfma_f32_32x32x16_bf16 v[80:95], v[228:231], v[124:127], v[80:95]
	ds_read_b128 v[204:207], v191 offset:45568
	ds_write_b128 v181, v[156:159] offset:45568
	s_waitcnt lgkmcnt(11)
	v_mfma_f32_32x32x16_bf16 v[80:95], v[232:235], v[120:123], v[80:95]
	ds_read_b128 v[224:227], v191 offset:45600
	v_add_u32_e32 v181, s4, v188
	ds_write_b128 v181, v[160:163] offset:32768
	s_waitcnt lgkmcnt(12)
	v_mfma_f32_32x32x16_bf16 v[80:95], v[236:239], v[116:119], v[80:95]
	ds_read_b128 v[228:231], v191 offset:45632
	s_add_i32 s5, s1, 2
	s_cmp_ge_u32 s5, s64
	s_cbranch_scc1 .Lfa_skipload
	v_subrev_u32_e32 v152, 32, v180
	v_ashrrev_i32_e32 v153, 31, v152
	v_ashrrev_i32_e32 v181, 31, v180
	v_lshlrev_b64 v[144:145], 12, v[152:153]
	v_lshlrev_b64 v[146:147], 12, v[180:181]
	s_movk_i32 s6, 0x1800
	v_lshl_add_u64 v[144:145], v[174:175], 0, v[144:145]
	v_lshl_add_u64 v[148:149], v[174:175], 0, v[146:147]
	v_mad_i64_i32 v[152:153], s[4:5], v152, s6, v[176:177]
	v_mad_i64_i32 v[156:157], s[4:5], v180, s6, v[176:177]
	v_mad_i64_i32 v[160:161], s[4:5], v190, s6, v[178:179]
	global_load_dwordx4 v[144:147], v[144:145], off
	s_nop 0
	global_load_dwordx4 v[148:151], v[148:149], off
	s_nop 0
	global_load_dwordx4 v[152:155], v[152:153], off
	s_nop 0
	global_load_dwordx4 v[156:159], v[156:157], off
	s_nop 0
	global_load_dwordx4 v[160:163], v[160:161], off offset:256
.Lfa_skipload:
	s_waitcnt lgkmcnt(12)
	v_mfma_f32_32x32x16_bf16 v[80:95], v[240:243], v[112:115], v[80:95]
	ds_read_b128 v[232:235], v191 offset:45664
	s_waitcnt lgkmcnt(12)
	v_mfma_f32_32x32x16_bf16 v[80:95], v[244:247], v[108:111], v[80:95]
	ds_read_b128 v[236:239], v191 offset:45696
	s_waitcnt lgkmcnt(12)
	v_mfma_f32_32x32x16_bf16 v[80:95], v[248:251], v[104:107], v[80:95]
	ds_read_b128 v[240:243], v191 offset:45728
	s_waitcnt lgkmcnt(11)
	v_mfma_f32_32x32x16_bf16 v[80:95], v[196:199], v[100:103], v[80:95]
	ds_read_b128 v[244:247], v191 offset:45760
	s_waitcnt lgkmcnt(10)
	v_mfma_f32_32x32x16_bf16 v[80:95], v[200:203], v[96:99], v[80:95]
	ds_read_b128 v[248:251], v191 offset:45792
	s_waitcnt lgkmcnt(9)
	v_mfma_f32_32x32x16_bf16 v[64:79], v[204:207], v[140:143], 0
	ds_read_b128 v[196:199], v191 offset:45824
	s_waitcnt lgkmcnt(8)
	v_mfma_f32_32x32x16_bf16 v[64:79], v[224:227], v[136:139], v[64:79]
	ds_read_b128 v[200:203], v191 offset:45856
	s_waitcnt lgkmcnt(7)
	v_mfma_f32_32x32x16_bf16 v[64:79], v[228:231], v[132:135], v[64:79]
	ds_read_b128 v[204:207], v191 offset:45888
	s_waitcnt lgkmcnt(7)
	v_mfma_f32_32x32x16_bf16 v[64:79], v[232:235], v[128:131], v[64:79]
	ds_read_b128 v[224:227], v191 offset:45920
	v_exp_f32_e32 v80, v80
	v_exp_f32_e32 v81, v81
	v_add_f32_e32 v192, 0, v80
	v_add_f32_e32 v192, v81, v192
	s_waitcnt lgkmcnt(7)
	v_mfma_f32_32x32x16_bf16 v[64:79], v[236:239], v[124:127], v[64:79]
	ds_read_b64_tr_b16 v[228:229], v194 offset:0
	ds_read_b64_tr_b16 v[230:231], v194 offset:2048
	v_exp_f32_e32 v82, v82
	v_exp_f32_e32 v83, v83
	v_add_f32_e32 v192, v82, v192
	v_add_f32_e32 v192, v83, v192
	s_waitcnt lgkmcnt(8)
	v_mfma_f32_32x32x16_bf16 v[64:79], v[240:243], v[120:123], v[64:79]
	ds_read_b64_tr_b16 v[232:233], v194 offset:4096
	ds_read_b64_tr_b16 v[234:235], v194 offset:6144
	v_exp_f32_e32 v84, v84
	v_exp_f32_e32 v85, v85
	v_add_f32_e32 v192, v84, v192
	v_add_f32_e32 v192, v85, v192
	s_waitcnt lgkmcnt(9)
; DEVI void finishSM(f32x16& p0, f32x16& p1, float alpha, float& l_reg, bf16x8& pa0, bf16x8& pa1, bf16x8& pa2, bf16x8& pa3) {
; #pragma unroll
;   for (int r = 0; r < 16; ++r) p1[r] = __builtin_amdgcn_exp2f(p1[r]);
;   float ps = 0;
; #pragma unroll
;   for (int r = 0; r < 16; ++r) ps += p0[r];
; #pragma unroll
;   for (int r = 0; r < 16; ++r) ps += p1[r];
;   { auto rr = __builtin_amdgcn_permlane32_swap(__float_as_uint(ps), __float_as_uint(ps), false, false);
;     ps = __uint_as_float(rr[0]) + __uint_as_float(rr[1]); }
;   l_reg = l_reg * alpha + ps;
;     ...
;   PK4(p0, 0, pa0); PK4(p0, 8, pa1); PK4(p1, 0, pa2); PK4(p1, 8, pa3);
;     ...
; }
; DEVI void qkt(f32x16& p0, f32x16& p1, const char* Ks, const bf16x8* qr, int r32, int hi) {
;   p0 = f32x16{}; p1 = f32x16{};
; #pragma unroll
;   for (int d0 = 0; d0 < 12; ++d0) { int cb = (d0 * 16 + hi * 8) * 2;
;     bf16x8 b0 = *reinterpret_cast<const bf16x8*>(Ks + KSWZ(r32, cb));
;     bf16x8 b1 = *reinterpret_cast<const bf16x8*>(Ks + KSWZ(32 + r32, cb));
;     p0 = __builtin_amdgcn_mfma_f32_32x32x16_bf16(b0, qr[d0], p0, 0, 0, 0);
;     p1 = __builtin_amdgcn_mfma_f32_32x32x16_bf16(b1, qr[d0], p1, 0, 0, 0); }
; }
; DEVI int v_st(int k, int c) { const int kk = (k & ~0xC) | ((k & 4) << 1) | ((k & 8) >> 1); return ((kk >> 3) * 4 + (c >> 5)) * 512 + ((kk & 7) * 32 + (c & 31)) * 2; }
; DEVI int v_rd_base(int lane) { return ((lane & 3) << 3) | (((lane >> 2) & 3) << 6) | (((lane >> 4) & 1) << 5) | (((lane >> 5) & 1) << 8); }
; template <int OFF> DEVI s16x4 tr_read(int vb) {
;   s16x4 r; asm volatile("ds_read_b64_tr_b16 %0, %1 offset:%2" : "=&v"(r) : "v"(vb), "i"(OFF) : "memory"); return r;
; }
; template <int D0> DEVI void pv_one(f32x16& od, int vb, bf16x8 pa0, bf16x8 pa1, bf16x8 pa2, bf16x8 pa3) {
;   const s16x4 l0 = tr_read<v_rd_off(D0, 0, 0)>(vb), h0 = tr_read<v_rd_off(D0, 0, 1)>(vb), l1 = tr_read<v_rd_off(D0, 1, 0)>(vb), h1 = tr_read<v_rd_off(D0, 1, 1)>(vb);
;   const s16x4 l2 = tr_read<v_rd_off(D0, 2, 0)>(vb), h2 = tr_read<v_rd_off(D0, 2, 1)>(vb), l3 = tr_read<v_rd_off(D0, 3, 0)>(vb), h3 = tr_read<v_rd_off(D0, 3, 1)>(vb);
;   asm volatile("s_waitcnt lgkmcnt(0)" ::: "memory"); SCHEDB();
;     ...
;   od = __builtin_amdgcn_mfma_f32_32x32x16_bf16(pa0, PK(l0, h0), od, 0, 0, 0);
;   od = __builtin_amdgcn_mfma_f32_32x32x16_bf16(pa1, PK(l1, h1), od, 0, 0, 0);
;   od = __builtin_amdgcn_mfma_f32_32x32x16_bf16(pa2, PK(l2, h2), od, 0, 0, 0);
	v_mfma_f32_32x32x16_bf16 v[64:79], v[244:247], v[116:119], v[64:79]
	ds_read_b64_tr_b16 v[236:237], v194 offset:8192
	ds_read_b64_tr_b16 v[238:239], v194 offset:10240
	v_exp_f32_e32 v86, v86
	v_exp_f32_e32 v87, v87
	v_add_f32_e32 v192, v86, v192
	v_add_f32_e32 v192, v87, v192
	s_waitcnt lgkmcnt(10)
	v_mfma_f32_32x32x16_bf16 v[64:79], v[248:251], v[112:115], v[64:79]
	ds_read_b64_tr_b16 v[240:241], v194 offset:12288
	ds_read_b64_tr_b16 v[242:243], v194 offset:14336
	v_exp_f32_e32 v88, v88
	v_exp_f32_e32 v89, v89
	v_add_f32_e32 v192, v88, v192
	v_add_f32_e32 v192, v89, v192
	s_waitcnt lgkmcnt(11)
	v_mfma_f32_32x32x16_bf16 v[64:79], v[196:199], v[108:111], v[64:79]
	ds_read_b64_tr_b16 v[244:245], v194 offset:512
	ds_read_b64_tr_b16 v[246:247], v194 offset:2560
	v_exp_f32_e32 v90, v90
	v_exp_f32_e32 v91, v91
	v_add_f32_e32 v192, v90, v192
	v_add_f32_e32 v192, v91, v192
	s_waitcnt lgkmcnt(12)
	v_mfma_f32_32x32x16_bf16 v[64:79], v[200:203], v[104:107], v[64:79]
	ds_read_b64_tr_b16 v[248:249], v194 offset:4608
	ds_read_b64_tr_b16 v[250:251], v194 offset:6656
	v_exp_f32_e32 v92, v92
	v_exp_f32_e32 v93, v93
	v_add_f32_e32 v192, v92, v192
	v_add_f32_e32 v192, v93, v192
	s_waitcnt lgkmcnt(13)
	v_mfma_f32_32x32x16_bf16 v[64:79], v[204:207], v[100:103], v[64:79]
	ds_read_b64_tr_b16 v[196:197], v194 offset:8704
	ds_read_b64_tr_b16 v[198:199], v194 offset:10752
	v_exp_f32_e32 v94, v94
	v_exp_f32_e32 v95, v95
	v_add_f32_e32 v192, v94, v192
	v_add_f32_e32 v192, v95, v192
	s_waitcnt lgkmcnt(14)
	v_mfma_f32_32x32x16_bf16 v[64:79], v[224:227], v[96:99], v[64:79]
	s_cmp_eq_u32 s1, 0
	s_cbranch_scc1 .Lfa_first
	s_waitcnt lgkmcnt(12)
	v_mfma_f32_32x32x16_bf16 v[0:15], v[208:211], v[228:231], v[0:15]
	ds_read_b64_tr_b16 v[200:201], v194 offset:12800
	ds_read_b64_tr_b16 v[202:203], v194 offset:14848
	s_waitcnt lgkmcnt(12)
	v_mfma_f32_32x32x16_bf16 v[0:15], v[212:215], v[232:235], v[0:15]
	ds_read_b64_tr_b16 v[204:205], v194 offset:1024
	ds_read_b64_tr_b16 v[206:207], v194 offset:3072
	s_waitcnt lgkmcnt(12)
	v_mfma_f32_32x32x16_bf16 v[0:15], v[216:219], v[236:239], v[0:15]
	ds_read_b64_tr_b16 v[224:225], v194 offset:5120
	ds_read_b64_tr_b16 v[226:227], v194 offset:7168
	s_waitcnt lgkmcnt(12)
	v_mfma_f32_32x32x16_bf16 v[0:15], v[220:223], v[240:243], v[0:15]
	ds_read_b64_tr_b16 v[228:229], v194 offset:9216
	ds_read_b64_tr_b16 v[230:231], v194 offset:11264
	v_exp_f32_e32 v64, v64
	v_exp_f32_e32 v65, v65
	v_add_f32_e32 v192, v64, v192
	v_add_f32_e32 v192, v65, v192
	s_waitcnt lgkmcnt(12)
	v_mfma_f32_32x32x16_bf16 v[16:31], v[208:211], v[244:247], v[16:31]
	ds_read_b64_tr_b16 v[232:233], v194 offset:13312
	ds_read_b64_tr_b16 v[234:235], v194 offset:15360
	v_exp_f32_e32 v66, v66
	v_exp_f32_e32 v67, v67
	v_add_f32_e32 v192, v66, v192
	v_add_f32_e32 v192, v67, v192
	s_waitcnt lgkmcnt(12)
	v_mfma_f32_32x32x16_bf16 v[16:31], v[212:215], v[248:251], v[16:31]
	ds_read_b64_tr_b16 v[236:237], v194 offset:1536
	ds_read_b64_tr_b16 v[238:239], v194 offset:3584
	v_exp_f32_e32 v68, v68
	v_exp_f32_e32 v69, v69
	v_add_f32_e32 v192, v68, v192
	v_add_f32_e32 v192, v69, v192
	s_waitcnt lgkmcnt(12)
	v_mfma_f32_32x32x16_bf16 v[16:31], v[216:219], v[196:199], v[16:31]
	ds_read_b64_tr_b16 v[240:241], v194 offset:5632
	ds_read_b64_tr_b16 v[242:243], v194 offset:7680
	v_exp_f32_e32 v70, v70
	v_exp_f32_e32 v71, v71
	v_add_f32_e32 v192, v70, v192
	v_add_f32_e32 v192, v71, v192
	s_waitcnt lgkmcnt(12)
	v_mfma_f32_32x32x16_bf16 v[16:31], v[220:223], v[200:203], v[16:31]
	ds_read_b64_tr_b16 v[244:245], v194 offset:9728
	ds_read_b64_tr_b16 v[246:247], v194 offset:11776
	v_exp_f32_e32 v72, v72
	v_exp_f32_e32 v73, v73
	v_add_f32_e32 v192, v72, v192
	v_add_f32_e32 v192, v73, v192
	s_waitcnt lgkmcnt(12)
	v_mfma_f32_32x32x16_bf16 v[32:47], v[208:211], v[204:207], v[32:47]
	ds_read_b64_tr_b16 v[248:249], v194 offset:13824
	ds_read_b64_tr_b16 v[250:251], v194 offset:15872
	v_exp_f32_e32 v74, v74
	v_exp_f32_e32 v75, v75
	v_add_f32_e32 v192, v74, v192
	v_add_f32_e32 v192, v75, v192
	s_waitcnt lgkmcnt(12)
	v_mfma_f32_32x32x16_bf16 v[32:47], v[212:215], v[224:227], v[32:47]
	v_exp_f32_e32 v76, v76
	v_exp_f32_e32 v77, v77
	v_add_f32_e32 v192, v76, v192
	v_add_f32_e32 v192, v77, v192
	s_waitcnt lgkmcnt(10)
	v_mfma_f32_32x32x16_bf16 v[32:47], v[216:219], v[228:231], v[32:47]
	v_exp_f32_e32 v78, v78
	v_exp_f32_e32 v79, v79
	v_add_f32_e32 v192, v78, v192
	v_add_f32_e32 v192, v79, v192
	s_waitcnt lgkmcnt(8)
	v_mfma_f32_32x32x16_bf16 v[32:47], v[220:223], v[232:235], v[32:47]
	v_mov_b32_e32 v193, v192
	s_waitcnt lgkmcnt(6)
	v_mfma_f32_32x32x16_bf16 v[48:63], v[208:211], v[236:239], v[48:63]
	v_permlane32_swap_b32_e32 v192, v193
	v_add_f32_e32 v192, v192, v193
	v_add_f32_e32 v173, v173, v192
	s_waitcnt lgkmcnt(4)
	v_mfma_f32_32x32x16_bf16 v[48:63], v[212:215], v[240:243], v[48:63]
	s_add_i32 s1, s1, 1
	v_add_u32_e32 v190, 64, v190
	v_add_u32_e32 v180, 64, v180
	s_waitcnt lgkmcnt(2)
	v_mfma_f32_32x32x16_bf16 v[48:63], v[216:219], v[244:247], v[48:63]
	s_waitcnt lgkmcnt(0)
	v_mfma_f32_32x32x16_bf16 v[48:63], v[220:223], v[248:251], v[48:63]
.Lfa_end:
	s_mov_b32 s100, s101
	s_waitcnt lgkmcnt(0)
	s_cmp_eq_u32 s0, s1
	s_barrier
	s_cbranch_scc1 .Lfa_drain
	s_branch .LBB0_121
; DEVI void finishSM(f32x16& p0, f32x16& p1, float alpha, float& l_reg, bf16x8& pa0, bf16x8& pa1, bf16x8& pa2, bf16x8& pa3) {
; #pragma unroll
;   for (int r = 0; r < 16; ++r) p1[r] = __builtin_amdgcn_exp2f(p1[r]);
;   float ps = 0;
; #pragma unroll
;   for (int r = 0; r < 16; ++r) ps += p0[r];
; #pragma unroll
;   for (int r = 0; r < 16; ++r) ps += p1[r];
;   { auto rr = __builtin_amdgcn_permlane32_swap(__float_as_uint(ps), __float_as_uint(ps), false, false);
;     ps = __uint_as_float(rr[0]) + __uint_as_float(rr[1]); }
;   l_reg = l_reg * alpha + ps;
;     ...
;   PK4(p0, 0, pa0); PK4(p0, 8, pa1); PK4(p1, 0, pa2); PK4(p1, 8, pa3);
;     ...
; }
; DEVI void qkt(f32x16& p0, f32x16& p1, const char* Ks, const bf16x8* qr, int r32, int hi) {
;   p0 = f32x16{}; p1 = f32x16{};
; #pragma unroll
;   for (int d0 = 0; d0 < 12; ++d0) { int cb = (d0 * 16 + hi * 8) * 2;
;     bf16x8 b0 = *reinterpret_cast<const bf16x8*>(Ks + KSWZ(r32, cb));
;     bf16x8 b1 = *reinterpret_cast<const bf16x8*>(Ks + KSWZ(32 + r32, cb));
;     p0 = __builtin_amdgcn_mfma_f32_32x32x16_bf16(b0, qr[d0], p0, 0, 0, 0);
;     p1 = __builtin_amdgcn_mfma_f32_32x32x16_bf16(b1, qr[d0], p1, 0, 0, 0); }
; }
; DEVI int v_st(int k, int c) { const int kk = (k & ~0xC) | ((k & 4) << 1) | ((k & 8) >> 1); return ((kk >> 3) * 4 + (c >> 5)) * 512 + ((kk & 7) * 32 + (c & 31)) * 2; }
; DEVI int v_rd_base(int lane) { return ((lane & 3) << 3) | (((lane >> 2) & 3) << 6) | (((lane >> 4) & 1) << 5) | (((lane >> 5) & 1) << 8); }
; template <int OFF> DEVI s16x4 tr_read(int vb) {
;   s16x4 r; asm volatile("ds_read_b64_tr_b16 %0, %1 offset:%2" : "=&v"(r) : "v"(vb), "i"(OFF) : "memory"); return r;
; }
; template <int D0> DEVI void pv_one(f32x16& od, int vb, bf16x8 pa0, bf16x8 pa1, bf16x8 pa2, bf16x8 pa3) {
;   const s16x4 l0 = tr_read<v_rd_off(D0, 0, 0)>(vb), h0 = tr_read<v_rd_off(D0, 0, 1)>(vb), l1 = tr_read<v_rd_off(D0, 1, 0)>(vb), h1 = tr_read<v_rd_off(D0, 1, 1)>(vb);
;   const s16x4 l2 = tr_read<v_rd_off(D0, 2, 0)>(vb), h2 = tr_read<v_rd_off(D0, 2, 1)>(vb), l3 = tr_read<v_rd_off(D0, 3, 0)>(vb), h3 = tr_read<v_rd_off(D0, 3, 1)>(vb);
;   asm volatile("s_waitcnt lgkmcnt(0)" ::: "memory"); SCHEDB();
;     ...
;   od = __builtin_amdgcn_mfma_f32_32x32x16_bf16(pa0, PK(l0, h0), od, 0, 0, 0);
;   od = __builtin_amdgcn_mfma_f32_32x32x16_bf16(pa1, PK(l1, h1), od, 0, 0, 0);
;   od = __builtin_amdgcn_mfma_f32_32x32x16_bf16(pa2, PK(l2, h2), od, 0, 0, 0);
.Lfa_first:
	s_nop 11
	v_exp_f32_e32 v64, v64
	v_exp_f32_e32 v65, v65
	v_add_f32_e32 v192, v64, v192
	v_add_f32_e32 v192, v65, v192
	v_exp_f32_e32 v66, v66
	v_exp_f32_e32 v67, v67
	v_add_f32_e32 v192, v66, v192
	v_add_f32_e32 v192, v67, v192
	v_exp_f32_e32 v68, v68
	v_exp_f32_e32 v69, v69
	v_add_f32_e32 v192, v68, v192
	v_add_f32_e32 v192, v69, v192
	v_exp_f32_e32 v70, v70
	v_exp_f32_e32 v71, v71
	v_add_f32_e32 v192, v70, v192
	v_add_f32_e32 v192, v71, v192
	v_exp_f32_e32 v72, v72
	v_exp_f32_e32 v73, v73
	v_add_f32_e32 v192, v72, v192
	v_add_f32_e32 v192, v73, v192
	v_exp_f32_e32 v74, v74
	v_exp_f32_e32 v75, v75
	v_add_f32_e32 v192, v74, v192
	v_add_f32_e32 v192, v75, v192
	v_exp_f32_e32 v76, v76
	v_exp_f32_e32 v77, v77
	v_add_f32_e32 v192, v76, v192
	v_add_f32_e32 v192, v77, v192
	v_exp_f32_e32 v78, v78
	v_exp_f32_e32 v79, v79
	v_add_f32_e32 v192, v78, v192
	v_add_f32_e32 v192, v79, v192
	v_mov_b32_e32 v193, v192
	s_nop 1
	v_permlane32_swap_b32_e32 v192, v193
	v_add_f32_e32 v192, v192, v193
	v_add_f32_e32 v173, v173, v192
	s_add_i32 s1, s1, 1
	v_add_u32_e32 v190, 64, v190
	v_add_u32_e32 v180, 64, v180
	s_branch .Lfa_end
.Lfa_drain:
	s_cmp_eq_u32 s100, 0x4000
	s_cselect_b32 s101, 0x15000, 0
	s_cmp_eq_u32 s100, 0
	s_cselect_b32 s101, 0x4000, s101
	v_add_u32_e32 v194, s101, v187
	ds_read_b64_tr_b16 v[196:197], v194 offset:0
	ds_read_b64_tr_b16 v[198:199], v194 offset:2048
	ds_read_b64_tr_b16 v[200:201], v194 offset:4096
	ds_read_b64_tr_b16 v[202:203], v194 offset:6144
	ds_read_b64_tr_b16 v[204:205], v194 offset:8192
	ds_read_b64_tr_b16 v[206:207], v194 offset:10240
	ds_read_b64_tr_b16 v[224:225], v194 offset:12288
	ds_read_b64_tr_b16 v[226:227], v194 offset:14336
	ds_read_b64_tr_b16 v[228:229], v194 offset:512
	ds_read_b64_tr_b16 v[230:231], v194 offset:2560
	v_cvt_pk_bf16_f32 v208, v80, v81
	v_cvt_pk_bf16_f32 v209, v82, v83
	v_cvt_pk_bf16_f32 v210, v84, v85
	v_cvt_pk_bf16_f32 v211, v86, v87
	v_cvt_pk_bf16_f32 v212, v88, v89
	v_cvt_pk_bf16_f32 v213, v90, v91
	v_cvt_pk_bf16_f32 v214, v92, v93
	v_cvt_pk_bf16_f32 v215, v94, v95
	v_cvt_pk_bf16_f32 v216, v64, v65
	v_cvt_pk_bf16_f32 v217, v66, v67
	v_cvt_pk_bf16_f32 v218, v68, v69
	v_cvt_pk_bf16_f32 v219, v70, v71
	v_cvt_pk_bf16_f32 v220, v72, v73
	v_cvt_pk_bf16_f32 v221, v74, v75
	v_cvt_pk_bf16_f32 v222, v76, v77
	v_cvt_pk_bf16_f32 v223, v78, v79
	s_nop 1
	v_permlane32_swap_b32_e32 v208, v210
	v_permlane32_swap_b32_e32 v209, v211
	v_permlane32_swap_b32_e32 v212, v214
	v_permlane32_swap_b32_e32 v213, v215
	v_permlane32_swap_b32_e32 v216, v218
	v_permlane32_swap_b32_e32 v217, v219
	v_permlane32_swap_b32_e32 v220, v222
	v_permlane32_swap_b32_e32 v221, v223
	s_nop 1
	s_waitcnt lgkmcnt(8)
	v_mfma_f32_32x32x16_bf16 v[0:15], v[208:211], v[196:199], v[0:15]
	ds_read_b64_tr_b16 v[232:233], v194 offset:4608
	ds_read_b64_tr_b16 v[234:235], v194 offset:6656
	s_waitcnt lgkmcnt(8)
	v_mfma_f32_32x32x16_bf16 v[0:15], v[212:215], v[200:203], v[0:15]
	ds_read_b64_tr_b16 v[236:237], v194 offset:8704
	ds_read_b64_tr_b16 v[238:239], v194 offset:10752
	s_waitcnt lgkmcnt(8)
	v_mfma_f32_32x32x16_bf16 v[0:15], v[216:219], v[204:207], v[0:15]
	ds_read_b64_tr_b16 v[240:241], v194 offset:12800
	ds_read_b64_tr_b16 v[242:243], v194 offset:14848
	s_waitcnt lgkmcnt(8)
	v_mfma_f32_32x32x16_bf16 v[0:15], v[220:223], v[224:227], v[0:15]
	ds_read_b64_tr_b16 v[244:245], v194 offset:1024
	ds_read_b64_tr_b16 v[246:247], v194 offset:3072
	s_waitcnt lgkmcnt(8)
	v_mfma_f32_32x32x16_bf16 v[16:31], v[208:211], v[228:231], v[16:31]
	ds_read_b64_tr_b16 v[248:249], v194 offset:5120
	ds_read_b64_tr_b16 v[250:251], v194 offset:7168
	s_waitcnt lgkmcnt(8)
	v_mfma_f32_32x32x16_bf16 v[16:31], v[212:215], v[232:235], v[16:31]
	ds_read_b64_tr_b16 v[196:197], v194 offset:9216
	ds_read_b64_tr_b16 v[198:199], v194 offset:11264
	s_waitcnt lgkmcnt(8)
	v_mfma_f32_32x32x16_bf16 v[16:31], v[216:219], v[236:239], v[16:31]
	ds_read_b64_tr_b16 v[200:201], v194 offset:13312
	ds_read_b64_tr_b16 v[202:203], v194 offset:15360
	s_waitcnt lgkmcnt(8)
	v_mfma_f32_32x32x16_bf16 v[16:31], v[220:223], v[240:243], v[16:31]
	ds_read_b64_tr_b16 v[204:205], v194 offset:1536
	ds_read_b64_tr_b16 v[206:207], v194 offset:3584
	s_waitcnt lgkmcnt(8)
	v_mfma_f32_32x32x16_bf16 v[32:47], v[208:211], v[244:247], v[32:47]
	ds_read_b64_tr_b16 v[224:225], v194 offset:5632
	ds_read_b64_tr_b16 v[226:227], v194 offset:7680
	s_waitcnt lgkmcnt(8)
	v_mfma_f32_32x32x16_bf16 v[32:47], v[212:215], v[248:251], v[32:47]
	ds_read_b64_tr_b16 v[228:229], v194 offset:9728
	ds_read_b64_tr_b16 v[230:231], v194 offset:11776
	s_waitcnt lgkmcnt(8)
	v_mfma_f32_32x32x16_bf16 v[32:47], v[216:219], v[196:199], v[32:47]
	ds_read_b64_tr_b16 v[232:233], v194 offset:13824
	ds_read_b64_tr_b16 v[234:235], v194 offset:15872
	s_waitcnt lgkmcnt(8)
	v_mfma_f32_32x32x16_bf16 v[32:47], v[220:223], v[200:203], v[32:47]
	s_waitcnt lgkmcnt(6)
	v_mfma_f32_32x32x16_bf16 v[48:63], v[208:211], v[204:207], v[48:63]
	s_waitcnt lgkmcnt(4)
	v_mfma_f32_32x32x16_bf16 v[48:63], v[212:215], v[224:227], v[48:63]
	s_waitcnt lgkmcnt(2)
	v_mfma_f32_32x32x16_bf16 v[48:63], v[216:219], v[228:231], v[48:63]
	s_waitcnt lgkmcnt(0)
	v_mfma_f32_32x32x16_bf16 v[48:63], v[220:223], v[232:235], v[48:63]
	s_mov_b32 s100, s101
	s_cmp_eq_u32 s100, 0x4000
	s_cselect_b32 s101, 0x15000, 0
	s_cmp_eq_u32 s100, 0
	s_cselect_b32 s101, 0x4000, s101
; DEVI void partialSM_fix(f32x16& p0, f32x16& p1) {
; #pragma unroll
;   for (int r = 0; r < 16; ++r) p0[r] = __builtin_amdgcn_exp2f(p0[r]);
; }
; DEVI void qkt(f32x16& p0, f32x16& p1, const char* Ks, const bf16x8* qr, int r32, int hi) {
;   p0 = f32x16{}; p1 = f32x16{};
; #pragma unroll
;   for (int d0 = 0; d0 < 12; ++d0) { int cb = (d0 * 16 + hi * 8) * 2;
;     bf16x8 b0 = *reinterpret_cast<const bf16x8*>(Ks + KSWZ(r32, cb));
;     bf16x8 b1 = *reinterpret_cast<const bf16x8*>(Ks + KSWZ(32 + r32, cb));
;     p0 = __builtin_amdgcn_mfma_f32_32x32x16_bf16(b0, qr[d0], p0, 0, 0, 0);
;     p1 = __builtin_amdgcn_mfma_f32_32x32x16_bf16(b1, qr[d0], p1, 0, 0, 0); }
; }
.LBB0_123:
	v_and_b32_e32 v64, 0x3fffffc0, v184
	v_mov_b32_e32 v65, 0x14800
	s_waitcnt vmcnt(0)
	v_lshl_add_u32 v144, v64, 2, v65
	s_and_b32 s0, s0, 1
	s_mul_i32 s1, s0, 0x6400
	v_or_b32_e32 v64, s1, v166
	v_add_u32_e32 v145, v64, v189
	ds_read_b128 v[64:67], v145 offset:32768
	v_add3_u32 v146, s1, v189, v166
	s_waitcnt lgkmcnt(0)
	v_mfma_f32_32x32x16_bf16 v[80:95], v[64:67], v[140:143], 0
	ds_read_b128 v[64:67], v146 offset:45568
	s_waitcnt lgkmcnt(0)
	v_mfma_f32_32x32x16_bf16 v[64:79], v[64:67], v[140:143], 0
	ds_read_b128 v[140:143], v145 offset:32800
	s_waitcnt lgkmcnt(0)
	v_mfma_f32_32x32x16_bf16 v[80:95], v[140:143], v[136:139], v[80:95]
	ds_read_b128 v[140:143], v146 offset:45600
	s_waitcnt lgkmcnt(0)
	v_mfma_f32_32x32x16_bf16 v[64:79], v[140:143], v[136:139], v[64:79]
	ds_read_b128 v[136:139], v145 offset:32832
	s_waitcnt lgkmcnt(0)
	v_mfma_f32_32x32x16_bf16 v[80:95], v[136:139], v[132:135], v[80:95]
	ds_read_b128 v[136:139], v146 offset:45632
	s_waitcnt lgkmcnt(0)
	v_mfma_f32_32x32x16_bf16 v[64:79], v[136:139], v[132:135], v[64:79]
	ds_read_b128 v[132:135], v145 offset:32864
	s_waitcnt lgkmcnt(0)
	v_mfma_f32_32x32x16_bf16 v[80:95], v[132:135], v[128:131], v[80:95]
	ds_read_b128 v[132:135], v146 offset:45664
	s_waitcnt lgkmcnt(0)
	v_mfma_f32_32x32x16_bf16 v[64:79], v[132:135], v[128:131], v[64:79]
	ds_read_b128 v[128:131], v145 offset:32896
	s_waitcnt lgkmcnt(0)
	v_mfma_f32_32x32x16_bf16 v[80:95], v[128:131], v[124:127], v[80:95]
	ds_read_b128 v[128:131], v146 offset:45696
	s_waitcnt lgkmcnt(0)
	v_mfma_f32_32x32x16_bf16 v[64:79], v[128:131], v[124:127], v[64:79]
	ds_read_b128 v[124:127], v145 offset:32928
	s_waitcnt lgkmcnt(0)
	v_mfma_f32_32x32x16_bf16 v[80:95], v[124:127], v[120:123], v[80:95]
	ds_read_b128 v[124:127], v146 offset:45728
	s_waitcnt lgkmcnt(0)
	v_mfma_f32_32x32x16_bf16 v[64:79], v[124:127], v[120:123], v[64:79]
	ds_read_b128 v[120:123], v145 offset:32960
	s_waitcnt lgkmcnt(0)
	v_mfma_f32_32x32x16_bf16 v[80:95], v[120:123], v[116:119], v[80:95]
	ds_read_b128 v[120:123], v146 offset:45760
	s_waitcnt lgkmcnt(0)
	v_mfma_f32_32x32x16_bf16 v[64:79], v[120:123], v[116:119], v[64:79]
	ds_read_b128 v[116:119], v145 offset:32992
	s_waitcnt lgkmcnt(0)
	v_mfma_f32_32x32x16_bf16 v[80:95], v[116:119], v[112:115], v[80:95]
	ds_read_b128 v[116:119], v146 offset:45792
	s_waitcnt lgkmcnt(0)
	v_mfma_f32_32x32x16_bf16 v[64:79], v[116:119], v[112:115], v[64:79]
	ds_read_b128 v[112:115], v145 offset:33024
	s_waitcnt lgkmcnt(0)
	v_mfma_f32_32x32x16_bf16 v[80:95], v[112:115], v[108:111], v[80:95]
	ds_read_b128 v[112:115], v146 offset:45824
	s_waitcnt lgkmcnt(0)
	v_mfma_f32_32x32x16_bf16 v[64:79], v[112:115], v[108:111], v[64:79]
	ds_read_b128 v[108:111], v145 offset:33056
	s_waitcnt lgkmcnt(0)
	v_mfma_f32_32x32x16_bf16 v[80:95], v[108:111], v[104:107], v[80:95]
	ds_read_b128 v[108:111], v145 offset:33088
	s_waitcnt lgkmcnt(0)
	v_mfma_f32_32x32x16_bf16 v[80:95], v[108:111], v[100:103], v[80:95]
	ds_read_b128 v[108:111], v145 offset:33120
	s_waitcnt lgkmcnt(0)
	v_mfma_f32_32x32x16_bf16 v[80:95], v[108:111], v[96:99], v[80:95]
	ds_read_b128 v[108:111], v146 offset:45856
	ds_read_b128 v[112:115], v146 offset:45888
	ds_read_b128 v[116:119], v146 offset:45920
	s_nop 8
	v_exp_f32_e32 v80, v80
	s_waitcnt lgkmcnt(2)
	v_mfma_f32_32x32x16_bf16 v[64:79], v[108:111], v[104:107], v[64:79]
	v_exp_f32_e32 v81, v81
	v_exp_f32_e32 v82, v82
	v_exp_f32_e32 v83, v83
	v_exp_f32_e32 v84, v84
	v_exp_f32_e32 v85, v85
	v_exp_f32_e32 v86, v86
	v_exp_f32_e32 v87, v87
	s_waitcnt lgkmcnt(1)
	v_mfma_f32_32x32x16_bf16 v[64:79], v[112:115], v[100:103], v[64:79]
	v_exp_f32_e32 v88, v88
	v_exp_f32_e32 v89, v89
	v_exp_f32_e32 v90, v90
	v_exp_f32_e32 v91, v91
	v_exp_f32_e32 v92, v92
	v_exp_f32_e32 v93, v93
	v_exp_f32_e32 v94, v94
	s_waitcnt lgkmcnt(0)
; DEVI void finishSM(f32x16& p0, f32x16& p1, float alpha, float& l_reg, bf16x8& pa0, bf16x8& pa1, bf16x8& pa2, bf16x8& pa3) {
; #pragma unroll
;   for (int r = 0; r < 16; ++r) p1[r] = __builtin_amdgcn_exp2f(p1[r]);
;   float ps = 0;
; #pragma unroll
;   for (int r = 0; r < 16; ++r) ps += p0[r];
; #pragma unroll
;   for (int r = 0; r < 16; ++r) ps += p1[r];
;   { auto rr = __builtin_amdgcn_permlane32_swap(__float_as_uint(ps), __float_as_uint(ps), false, false);
;     ps = __uint_as_float(rr[0]) + __uint_as_float(rr[1]); }
;   l_reg = l_reg * alpha + ps;
;     ...
;   PK4(p0, 0, pa0); PK4(p0, 8, pa1); PK4(p1, 0, pa2); PK4(p1, 8, pa3);
;     ...
; }
; DEVI void qkt(f32x16& p0, f32x16& p1, const char* Ks, const bf16x8* qr, int r32, int hi) {
;   p0 = f32x16{}; p1 = f32x16{};
; #pragma unroll
;   for (int d0 = 0; d0 < 12; ++d0) { int cb = (d0 * 16 + hi * 8) * 2;
;     bf16x8 b0 = *reinterpret_cast<const bf16x8*>(Ks + KSWZ(r32, cb));
;     bf16x8 b1 = *reinterpret_cast<const bf16x8*>(Ks + KSWZ(32 + r32, cb));
;     p0 = __builtin_amdgcn_mfma_f32_32x32x16_bf16(b0, qr[d0], p0, 0, 0, 0);
;     p1 = __builtin_amdgcn_mfma_f32_32x32x16_bf16(b1, qr[d0], p1, 0, 0, 0); }
; }
; DEVI int v_st(int k, int c) { const int kk = (k & ~0xC) | ((k & 4) << 1) | ((k & 8) >> 1); return ((kk >> 3) * 4 + (c >> 5)) * 512 + ((kk & 7) * 32 + (c & 31)) * 2; }
; DEVI int v_rd_base(int lane) { return ((lane & 3) << 3) | (((lane >> 2) & 3) << 6) | (((lane >> 4) & 1) << 5) | (((lane >> 5) & 1) << 8); }
; template <int OFF> DEVI s16x4 tr_read(int vb) {
;   s16x4 r; asm volatile("ds_read_b64_tr_b16 %0, %1 offset:%2" : "=&v"(r) : "v"(vb), "i"(OFF) : "memory"); return r;
; }
; template <int D0> DEVI void pv_one(f32x16& od, int vb, bf16x8 pa0, bf16x8 pa1, bf16x8 pa2, bf16x8 pa3) {
;   const s16x4 l0 = tr_read<v_rd_off(D0, 0, 0)>(vb), h0 = tr_read<v_rd_off(D0, 0, 1)>(vb), l1 = tr_read<v_rd_off(D0, 1, 0)>(vb), h1 = tr_read<v_rd_off(D0, 1, 1)>(vb);
;   const s16x4 l2 = tr_read<v_rd_off(D0, 2, 0)>(vb), h2 = tr_read<v_rd_off(D0, 2, 1)>(vb), l3 = tr_read<v_rd_off(D0, 3, 0)>(vb), h3 = tr_read<v_rd_off(D0, 3, 1)>(vb);
;   asm volatile("s_waitcnt lgkmcnt(0)" ::: "memory"); SCHEDB();
;     ...
;   od = __builtin_amdgcn_mfma_f32_32x32x16_bf16(pa0, PK(l0, h0), od, 0, 0, 0);
;   od = __builtin_amdgcn_mfma_f32_32x32x16_bf16(pa1, PK(l1, h1), od, 0, 0, 0);
;   od = __builtin_amdgcn_mfma_f32_32x32x16_bf16(pa2, PK(l2, h2), od, 0, 0, 0);
	v_mfma_f32_32x32x16_bf16 v[64:79], v[116:119], v[96:99], v[64:79]
	v_exp_f32_e32 v95, v95
	s_nop 10
	v_exp_f32_e32 v96, v64
	v_add_f32_e32 v64, 0, v80
	v_add_f32_e32 v64, v81, v64
	v_add_f32_e32 v64, v82, v64
	v_add_f32_e32 v64, v83, v64
	v_add_f32_e32 v64, v84, v64
	v_add_f32_e32 v64, v85, v64
	v_add_f32_e32 v64, v86, v64
	v_add_f32_e32 v64, v87, v64
	v_add_f32_e32 v64, v88, v64
	v_add_f32_e32 v64, v89, v64
	v_add_f32_e32 v64, v90, v64
	v_add_f32_e32 v64, v91, v64
	v_add_f32_e32 v64, v92, v64
	v_exp_f32_e32 v97, v65
	v_add_f32_e32 v64, v93, v64
	v_exp_f32_e32 v98, v66
	v_add_f32_e32 v64, v94, v64
	v_exp_f32_e32 v99, v67
	v_add_f32_e32 v64, v95, v64
	v_exp_f32_e32 v100, v68
	v_add_f32_e32 v64, v96, v64
	v_exp_f32_e32 v101, v69
	v_add_f32_e32 v64, v97, v64
	v_exp_f32_e32 v102, v70
	v_add_f32_e32 v64, v98, v64
	v_exp_f32_e32 v103, v71
	v_add_f32_e32 v64, v99, v64
	v_exp_f32_e32 v104, v72
	v_add_f32_e32 v64, v100, v64
	v_exp_f32_e32 v105, v73
	v_add_f32_e32 v64, v101, v64
	v_exp_f32_e32 v106, v74
	v_add_f32_e32 v64, v102, v64
	v_exp_f32_e32 v107, v75
	v_add_f32_e32 v64, v103, v64
	v_exp_f32_e32 v108, v76
	v_add_f32_e32 v64, v104, v64
	v_exp_f32_e32 v109, v77
	v_add_f32_e32 v64, v105, v64
	v_exp_f32_e32 v110, v78
	v_add_f32_e32 v64, v106, v64
	v_exp_f32_e32 v111, v79
	v_add_f32_e32 v64, v107, v64
	v_add_f32_e32 v64, v108, v64
	v_add_f32_e32 v64, v109, v64
	v_add_f32_e32 v64, v110, v64
	v_add_f32_e32 v64, v111, v64
	v_mov_b32_e32 v65, v64
	s_nop 1
	v_permlane32_swap_b32_e32 v64, v65
	v_cvt_pk_bf16_f32 v66, v80, v81
	v_cvt_pk_bf16_f32 v67, v82, v83
	v_cvt_pk_bf16_f32 v68, v84, v85
	v_cvt_pk_bf16_f32 v69, v86, v87
	v_cvt_pk_bf16_f32 v70, v88, v89
	v_cvt_pk_bf16_f32 v71, v90, v91
	v_cvt_pk_bf16_f32 v72, v92, v93
	v_cvt_pk_bf16_f32 v73, v94, v95
	v_cvt_pk_bf16_f32 v74, v96, v97
	v_cvt_pk_bf16_f32 v75, v98, v99
	v_cvt_pk_bf16_f32 v76, v100, v101
	v_cvt_pk_bf16_f32 v77, v102, v103
	v_cvt_pk_bf16_f32 v78, v104, v105
	v_cvt_pk_bf16_f32 v79, v106, v107
	v_cvt_pk_bf16_f32 v80, v108, v109
	v_cvt_pk_bf16_f32 v81, v110, v111
	s_nop 0
	v_permlane32_swap_b32_e32 v66, v68
	v_permlane32_swap_b32_e32 v67, v69
	v_permlane32_swap_b32_e32 v70, v72
	v_permlane32_swap_b32_e32 v71, v73
	v_permlane32_swap_b32_e32 v74, v76
	v_permlane32_swap_b32_e32 v75, v77
	v_permlane32_swap_b32_e32 v78, v80
	v_permlane32_swap_b32_e32 v79, v81
	s_setprio 1
	v_add_u32_e32 v98, s101, v187
	ds_read_b64_tr_b16 v[82:83], v98 offset:0
	ds_read_b64_tr_b16 v[84:85], v98 offset:0x800
	ds_read_b64_tr_b16 v[86:87], v98 offset:0x1000
	ds_read_b64_tr_b16 v[88:89], v98 offset:0x1800
	ds_read_b64_tr_b16 v[90:91], v98 offset:0x2000
	ds_read_b64_tr_b16 v[92:93], v98 offset:0x2800
	ds_read_b64_tr_b16 v[94:95], v98 offset:0x3000
	ds_read_b64_tr_b16 v[96:97], v98 offset:0x3800
	s_waitcnt lgkmcnt(0)
	s_nop 0
	v_mfma_f32_32x32x16_bf16 v[0:15], v[66:69], v[82:85], v[0:15]
	ds_read_b64_tr_b16 v[82:83], v98 offset:0x200
	ds_read_b64_tr_b16 v[84:85], v98 offset:0xa00
	v_mfma_f32_32x32x16_bf16 v[0:15], v[70:73], v[86:89], v[0:15]
	ds_read_b64_tr_b16 v[86:87], v98 offset:0x1200
	ds_read_b64_tr_b16 v[88:89], v98 offset:0x1a00
	v_mfma_f32_32x32x16_bf16 v[0:15], v[74:77], v[90:93], v[0:15]
	ds_read_b64_tr_b16 v[90:91], v98 offset:0x2200
	ds_read_b64_tr_b16 v[92:93], v98 offset:0x2a00
	v_mfma_f32_32x32x16_bf16 v[0:15], v[78:81], v[94:97], v[0:15]
	ds_read_b64_tr_b16 v[94:95], v98 offset:0x3200
	ds_read_b64_tr_b16 v[96:97], v98 offset:0x3a00
	s_waitcnt lgkmcnt(0)
	v_mfma_f32_32x32x16_bf16 v[16:31], v[66:69], v[82:85], v[16:31]
	ds_read_b64_tr_b16 v[82:83], v98 offset:0x400
	ds_read_b64_tr_b16 v[84:85], v98 offset:0xc00
	v_mfma_f32_32x32x16_bf16 v[16:31], v[70:73], v[86:89], v[16:31]
	ds_read_b64_tr_b16 v[86:87], v98 offset:0x1400
	ds_read_b64_tr_b16 v[88:89], v98 offset:0x1c00
	v_mfma_f32_32x32x16_bf16 v[16:31], v[74:77], v[90:93], v[16:31]
	ds_read_b64_tr_b16 v[90:91], v98 offset:0x2400
	ds_read_b64_tr_b16 v[92:93], v98 offset:0x2c00
	v_mfma_f32_32x32x16_bf16 v[16:31], v[78:81], v[94:97], v[16:31]
	ds_read_b64_tr_b16 v[94:95], v98 offset:0x3400
	ds_read_b64_tr_b16 v[96:97], v98 offset:0x3c00
	s_waitcnt lgkmcnt(0)
	v_mfma_f32_32x32x16_bf16 v[32:47], v[66:69], v[82:85], v[32:47]
	ds_read_b64_tr_b16 v[82:83], v98 offset:0x600
	ds_read_b64_tr_b16 v[84:85], v98 offset:0xe00
	v_mfma_f32_32x32x16_bf16 v[32:47], v[70:73], v[86:89], v[32:47]
	ds_read_b64_tr_b16 v[86:87], v98 offset:0x1600
	ds_read_b64_tr_b16 v[88:89], v98 offset:0x1e00
	v_mfma_f32_32x32x16_bf16 v[32:47], v[74:77], v[90:93], v[32:47]
	ds_read_b64_tr_b16 v[90:91], v98 offset:0x2600
	ds_read_b64_tr_b16 v[92:93], v98 offset:0x2e00
	v_mfma_f32_32x32x16_bf16 v[32:47], v[78:81], v[94:97], v[32:47]
	ds_read_b64_tr_b16 v[94:95], v98 offset:0x3600
	ds_read_b64_tr_b16 v[96:97], v98 offset:0x3e00
	s_waitcnt lgkmcnt(0)
	v_mfma_f32_32x32x16_bf16 v[48:63], v[66:69], v[82:85], v[48:63]
	v_mfma_f32_32x32x16_bf16 v[48:63], v[70:73], v[86:89], v[48:63]
	v_mfma_f32_32x32x16_bf16 v[48:63], v[74:77], v[90:93], v[48:63]
	v_mfma_f32_32x32x16_bf16 v[48:63], v[78:81], v[94:97], v[48:63]
	s_setprio 0
	v_cmp_gt_u32_e32 vcc, 32, v171
	s_barrier
	s_and_saveexec_b64 s[0:1], vcc
	s_cbranch_execz .LBB0_94
	v_add_f32_e32 v64, v64, v65
	v_lshl_add_u32 v66, v182, 2, v144
	v_add_f32_e32 v64, v173, v64
	ds_write_b32 v66, v64
	s_branch .LBB0_94

; DEVI int nblk() { int n = NBLK; asm volatile("" : "+s"(n)); return n; }
; DEVI int obid() { int b = blockIdx.x; asm volatile("" : "+s"(b)); return b; }
; DEVI int otid() { int t = threadIdx.x; asm volatile("" : "+v"(t)); return t; }
; DEVI void phase_rmsnorm(const float* __restrict__ x, const float* __restrict__ g, bfr* __restrict__ h, const float* __restrict__ xp = nullptr, const float* __restrict__ xs = nullptr) {
;   const int tid_ = otid(), wid = tid_ >> 6, lane = tid_ & 63;
;   for (int t = obid() * 8 + wid; t < T; t += nblk() * 8) {
;     const f32x4* xr = (const f32x4*)(xp ? (t < 16384 ? xp + (long)t * DM : xs + (long)(t - 16384) * DM) : x + (long)t * DM);
;     f32x4 v[8]; float ss = 0;
; #pragma unroll
;     for (int i = 0; i < 4; ++i) { v[2 * i] = xr[i * 128 + lane * 2]; v[2 * i + 1] = xr[i * 128 + lane * 2 + 1]; }
; #pragma unroll
;     for (int i = 0; i < 8; ++i) ss += v[i][0] * v[i][0] + v[i][1] * v[i][1] + v[i][2] * v[i][2] + v[i][3] * v[i][3];
;     ss = wave_sum(ss);
;     const float r = rsqrtf(ss * (1.f / DM) + EPS);
; #pragma unroll
;     for (int i = 0; i < 4; ++i) { const f32x4 g0 = ((const f32x4*)g)[i * 128 + lane * 2], g1 = ((const f32x4*)g)[i * 128 + lane * 2 + 1];
.LBB0_203:
	s_andn2_b64 vcc, exec, s[0:1]
	s_cbranch_vccnz .LBB0_268
	v_readlane_b32 s0, v255, 32
	s_cmp_lg_u32 s0, 0
	s_cbranch_scc1 .LBB0_268
	v_readlane_b32 s0, v255, 19
	v_readlane_b32 s1, v255, 20
	s_add_i32 s0, s0, 15
	s_cmp_gt_u32 s0, 32
	s_mov_b64 s[0:1], -1
	s_cbranch_scc0 .LBB0_210
	v_mov_b32_e32 v0, v164
	s_mov_b32 s0, s56
	s_nop 0
	v_ashrrev_i32_e32 v1, 6, v0
	v_lshl_add_u32 v40, s0, 3, v1
	s_mov_b32 s0, 0x8000
	v_cmp_gt_i32_e32 vcc, s0, v40
	s_and_saveexec_b64 s[0:1], vcc
	v_readlane_b32 s8, v255, 2
	v_readlane_b32 s10, v255, 4
	v_readlane_b32 s11, v255, 5
	s_mov_b32 s6, 0x800000
	s_movk_i32 s7, 0x7fff
	v_readlane_b32 s9, v255, 3
	s_cbranch_execz .LBB0_209
	v_readlane_b32 s4, v255, 21
	v_readlane_b32 s5, v255, 22
	s_lshl_b32 s4, s4, 11
	s_ashr_i32 s5, s4, 31
	s_lshl_b64 s[4:5], s[4:5], 2
	v_and_b32_e32 v8, 63, v0
	s_add_u32 s4, s16, s4
	v_lshlrev_b32_e32 v166, 4, v8
	s_addc_u32 s5, s17, s5
	v_lshl_add_u64 v[42:43], s[84:85], 0, v[166:167]
	v_lshlrev_b32_e32 v166, 5, v8
	global_load_dwordx4 v[0:3], v166, s[4:5]
	global_load_dwordx4 v[4:7], v166, s[4:5] offset:16
	v_and_b32_e32 v9, 64, v169
	v_add_u32_e32 v9, 64, v9
	v_xor_b32_e32 v10, 32, v169
	v_cmp_lt_i32_e32 vcc, v10, v9
	v_lshlrev_b32_e32 v8, 1, v8
	v_lshl_add_u64 v[44:45], s[4:5], 0, v[166:167]
	v_cndmask_b32_e32 v10, v169, v10, vcc
	v_lshlrev_b32_e32 v56, 2, v10
	v_xor_b32_e32 v10, 16, v169
	v_cmp_lt_i32_e32 vcc, v10, v9
	v_or_b32_e32 v12, 0x180, v8
	v_lshlrev_b32_e32 v52, 4, v12
	v_cndmask_b32_e32 v10, v169, v10, vcc
	v_lshlrev_b32_e32 v57, 2, v10
	v_xor_b32_e32 v10, 8, v169
	v_cmp_lt_i32_e32 vcc, v10, v9
	s_nop 1
	v_cndmask_b32_e32 v10, v169, v10, vcc
	v_lshlrev_b32_e32 v58, 2, v10
	v_xor_b32_e32 v10, 4, v169
	v_cmp_lt_i32_e32 vcc, v10, v9
	s_nop 1
	v_cndmask_b32_e32 v10, v169, v10, vcc
	v_lshlrev_b32_e32 v59, 2, v10
	v_xor_b32_e32 v10, 2, v169
	v_cmp_lt_i32_e32 vcc, v10, v9
	s_nop 1
	v_cndmask_b32_e32 v10, v169, v10, vcc
	v_lshlrev_b32_e32 v60, 2, v10
	v_xor_b32_e32 v10, 1, v169
	v_cmp_lt_i32_e32 vcc, v10, v9
	s_nop 1
	v_cndmask_b32_e32 v9, v169, v10, vcc
	v_or_b32_e32 v10, 0x100, v8
	v_lshlrev_b32_e32 v166, 4, v10
	v_lshl_add_u64 v[46:47], s[4:5], 0, v[166:167]
	v_lshlrev_b32_e32 v166, 4, v12
	v_lshlrev_b32_e32 v61, 2, v9
	v_lshl_add_u64 v[48:49], s[4:5], 0, v[166:167]
	s_mov_b64 s[4:5], 0
	v_lshlrev_b32_e32 v166, 4, v8
	v_lshlrev_b32_e32 v50, 4, v10
	global_load_dwordx4 v[208:211], v[44:45], off offset:2048
	global_load_dwordx4 v[212:215], v[44:45], off offset:2064
	global_load_dwordx4 v[216:219], v[46:47], off
	global_load_dwordx4 v[220:223], v[46:47], off offset:16
	global_load_dwordx4 v[224:227], v[48:49], off
	global_load_dwordx4 v[228:231], v[48:49], off offset:16
; DEVI unsigned cvtpk(float lo, float hi) { unsigned r; asm volatile("v_cvt_pk_bf16_f32 %0, %1, %2" : "=v"(r) : "v"(lo), "v"(hi)); return r; }
; DEVI int nblk() { int n = NBLK; asm volatile("" : "+s"(n)); return n; }
; DEVI int obid() { int b = blockIdx.x; asm volatile("" : "+s"(b)); return b; }
; DEVI void phase_rmsnorm(const float* __restrict__ x, const float* __restrict__ g, bfr* __restrict__ h, const float* __restrict__ xp = nullptr, const float* __restrict__ xs = nullptr) {
;     ...
;   for (int t = obid() * 8 + wid; t < T; t += nblk() * 8) {
;     const f32x4* xr = (const f32x4*)(xp ? (t < 16384 ? xp + (long)t * DM : xs + (long)(t - 16384) * DM) : x + (long)t * DM);
;     f32x4 v[8]; float ss = 0;
; #pragma unroll
;     for (int i = 0; i < 4; ++i) { v[2 * i] = xr[i * 128 + lane * 2]; v[2 * i + 1] = xr[i * 128 + lane * 2 + 1]; }
; #pragma unroll
;     for (int i = 0; i < 8; ++i) ss += v[i][0] * v[i][0] + v[i][1] * v[i][1] + v[i][2] * v[i][2] + v[i][3] * v[i][3];
;     ss = wave_sum(ss);
;     const float r = rsqrtf(ss * (1.f / DM) + EPS);
; #pragma unroll
;     for (int i = 0; i < 4; ++i) { const f32x4 g0 = ((const f32x4*)g)[i * 128 + lane * 2], g1 = ((const f32x4*)g)[i * 128 + lane * 2 + 1];
;       const f32x4 a = v[2 * i], c = v[2 * i + 1];
;       u32x4 w = {cvtpk(a[0] * r * g0[0], a[1] * r * g0[1]), cvtpk(a[2] * r * g0[2], a[3] * r * g0[3]),
;                  cvtpk(c[0] * r * g1[0], c[1] * r * g1[1]), cvtpk(c[2] * r * g1[2], c[3] * r * g1[3])};
;       *reinterpret_cast<u32x4*>(h + (long)t * DM + i * 512 + lane * 8) = w; }
;   }
.LBB0_208:
	v_ashrrev_i32_e32 v41, 31, v40
	v_lshlrev_b64 v[8:9], 13, v[40:41]
	v_lshl_add_u64 v[8:9], s[10:11], 0, v[8:9]
	v_lshl_add_u64 v[10:11], v[8:9], 0, v[166:167]
	global_load_dwordx4 v[32:35], v[10:11], off offset:16
	global_load_dwordx4 v[36:39], v[10:11], off
	global_load_dwordx4 v[24:27], v[10:11], off offset:2064
	global_load_dwordx4 v[28:31], v[10:11], off offset:2048
	v_mov_b32_e32 v51, v167
	v_lshl_add_u64 v[10:11], v[8:9], 0, v[50:51]
	global_load_dwordx4 v[20:23], v[10:11], off
	global_load_dwordx4 v[16:19], v[10:11], off offset:16
	v_mov_b32_e32 v53, v167
	v_lshl_add_u64 v[8:9], v[8:9], 0, v[52:53]
	global_load_dwordx4 v[12:15], v[8:9], off
	s_nop 0
	global_load_dwordx4 v[8:11], v[8:9], off offset:16
	s_movk_i32 s2, 0x100
	s_waitcnt vmcnt(0)
	v_mul_f32_e32 v53, v33, v33
	v_mul_f32_e32 v51, v37, v37
	v_fmac_f32_e32 v51, v36, v36
	v_fmac_f32_e32 v53, v32, v32
	v_fmac_f32_e32 v51, v38, v38
	v_fmac_f32_e32 v53, v34, v34
	v_fmac_f32_e32 v51, v39, v39
	v_fmac_f32_e32 v53, v35, v35
	v_add_f32_e32 v51, v51, v53
	v_mul_f32_e32 v53, v29, v29
	v_fmac_f32_e32 v53, v28, v28
	v_fmac_f32_e32 v53, v30, v30
	v_fmac_f32_e32 v53, v31, v31
	v_add_f32_e32 v51, v51, v53
	v_mul_f32_e32 v53, v25, v25
	v_mov_b32_e32 v62, v21
	v_mov_b32_e32 v63, v17
	v_fmac_f32_e32 v53, v24, v24
	v_mov_b32_e32 v54, v20
	v_mov_b32_e32 v55, v16
	v_pk_mul_f32 v[62:63], v[62:63], v[62:63]
	v_fmac_f32_e32 v53, v26, v26
	v_pk_fma_f32 v[54:55], v[54:55], v[54:55], v[62:63]
	v_mov_b32_e32 v62, v22
	v_mov_b32_e32 v63, v18
	v_fmac_f32_e32 v53, v27, v27
	v_pk_fma_f32 v[54:55], v[62:63], v[62:63], v[54:55]
	v_mov_b32_e32 v62, v23
	v_mov_b32_e32 v63, v19
	v_add_f32_e32 v51, v51, v53
	v_pk_fma_f32 v[54:55], v[62:63], v[62:63], v[54:55]
	v_mov_b32_e32 v62, v13
	v_add_f32_e32 v51, v51, v54
	v_mov_b32_e32 v63, v9
	v_add_f32_e32 v51, v51, v55
	v_mov_b32_e32 v54, v12
	v_mov_b32_e32 v55, v8
	v_pk_mul_f32 v[62:63], v[62:63], v[62:63]
	s_nop 0
	v_pk_fma_f32 v[54:55], v[54:55], v[54:55], v[62:63]
	v_mov_b32_e32 v62, v14
	v_mov_b32_e32 v63, v10
	v_pk_fma_f32 v[54:55], v[62:63], v[62:63], v[54:55]
	v_mov_b32_e32 v62, v15
	v_mov_b32_e32 v63, v11
	v_pk_fma_f32 v[54:55], v[62:63], v[62:63], v[54:55]
	s_nop 0
	v_add_f32_e32 v51, v51, v54
	v_add_f32_e32 v51, v51, v55
	ds_bpermute_b32 v53, v56, v51
	v_lshlrev_b64 v[54:55], 12, v[40:41]
	v_lshl_add_u64 v[54:55], v[42:43], 0, v[54:55]
	s_waitcnt lgkmcnt(0)
	v_add_f32_e32 v51, v51, v53
	ds_bpermute_b32 v53, v57, v51
	s_waitcnt lgkmcnt(0)
	v_add_f32_e32 v51, v51, v53
	ds_bpermute_b32 v53, v58, v51
	s_waitcnt lgkmcnt(0)
	v_add_f32_e32 v51, v51, v53
	ds_bpermute_b32 v53, v59, v51
	s_waitcnt lgkmcnt(0)
	v_add_f32_e32 v51, v51, v53
	ds_bpermute_b32 v53, v60, v51
	s_waitcnt lgkmcnt(0)
	v_add_f32_e32 v51, v51, v53
	ds_bpermute_b32 v53, v61, v51
	s_waitcnt lgkmcnt(0)
	v_add_f32_e32 v51, v51, v53
	v_fmamk_f32 v51, v51, 0x3a000000, v168
	v_cmp_gt_f32_e32 vcc, s6, v51
	v_mul_f32_e32 v53, 0x4b800000, v51
	s_nop 0
	v_cndmask_b32_e32 v51, v51, v53, vcc
	v_rsq_f32_e32 v51, v51
	s_nop 0
	v_mul_f32_e32 v53, 0x45800000, v51
	v_cndmask_b32_e32 v51, v51, v53, vcc
	v_mul_f32_e32 v36, v36, v51
	v_mul_f32_e32 v37, v37, v51
	v_mul_f32_e32 v36, v0, v36
	v_mul_f32_e32 v37, v1, v37
	v_cvt_pk_bf16_f32 v36, v36, v37
	v_mul_f32_e32 v37, v38, v51
	v_mul_f32_e32 v38, v39, v51
	v_mul_f32_e32 v32, v32, v51
	v_mul_f32_e32 v33, v33, v51
	v_mul_f32_e32 v37, v2, v37
	v_mul_f32_e32 v38, v3, v38
	v_mul_f32_e32 v32, v4, v32
	v_mul_f32_e32 v33, v5, v33
	v_cvt_pk_bf16_f32 v37, v37, v38
	v_cvt_pk_bf16_f32 v38, v32, v33
	v_mul_f32_e32 v32, v34, v51
	v_mul_f32_e32 v33, v35, v51
	v_mul_f32_e32 v32, v6, v32
	v_mul_f32_e32 v33, v7, v33
	v_cvt_pk_bf16_f32 v39, v32, v33
	global_store_dwordx4 v[54:55], v[36:39], off
	v_mul_f32_e32 v28, v28, v51
	v_mul_f32_e32 v29, v29, v51
	v_mul_f32_e32 v24, v24, v51
	v_mul_f32_e32 v25, v25, v51
	v_mul_f32_e32 v20, v20, v51
	v_mul_f32_e32 v21, v21, v51
	v_mul_f32_e32 v16, v16, v51
	v_mul_f32_e32 v17, v17, v51
	v_mul_f32_e32 v12, v12, v51
	v_mul_f32_e32 v13, v13, v51
	v_mul_f32_e32 v8, v8, v51
	v_mul_f32_e32 v9, v9, v51
	v_mul_f32_e32 v24, v212, v24
	v_mul_f32_e32 v28, v208, v28
	v_mul_f32_e32 v29, v209, v29
	v_cvt_pk_bf16_f32 v28, v28, v29
	v_mul_f32_e32 v29, v30, v51
	v_mul_f32_e32 v30, v31, v51
	v_mul_f32_e32 v29, v210, v29
	v_mul_f32_e32 v30, v211, v30
	v_mul_f32_e32 v25, v213, v25
	v_cvt_pk_bf16_f32 v29, v29, v30
	v_cvt_pk_bf16_f32 v30, v24, v25
	v_mul_f32_e32 v24, v26, v51
	v_mul_f32_e32 v25, v27, v51
	v_mul_f32_e32 v24, v214, v24
	v_mul_f32_e32 v25, v215, v25
	v_cvt_pk_bf16_f32 v31, v24, v25
	global_store_dwordx4 v[54:55], v[28:31], off offset:1024
	v_mul_f32_e32 v16, v16, v220
	v_mul_f32_e32 v20, v20, v216
	v_mul_f32_e32 v21, v21, v217
	v_cvt_pk_bf16_f32 v20, v20, v21
	v_mul_f32_e32 v21, v22, v51
	v_mul_f32_e32 v22, v23, v51
	v_mul_f32_e32 v21, v21, v218
	v_mul_f32_e32 v22, v22, v219
	v_mul_f32_e32 v17, v17, v221
	v_cvt_pk_bf16_f32 v21, v21, v22
	v_cvt_pk_bf16_f32 v22, v16, v17
	v_mul_f32_e32 v16, v18, v51
	v_mul_f32_e32 v17, v19, v51
	v_mul_f32_e32 v16, v16, v222
	v_mul_f32_e32 v17, v17, v223
	v_cvt_pk_bf16_f32 v23, v16, v17
	global_store_dwordx4 v[54:55], v[20:23], off offset:2048
	v_mul_f32_e32 v8, v8, v228
	v_mul_f32_e32 v12, v12, v224
	v_mul_f32_e32 v13, v13, v225
	v_cvt_pk_bf16_f32 v12, v12, v13
	v_mul_f32_e32 v13, v14, v51
	v_mul_f32_e32 v14, v15, v51
	v_mul_f32_e32 v13, v13, v226
	v_mul_f32_e32 v14, v14, v227
	v_mul_f32_e32 v9, v9, v229
	v_cvt_pk_bf16_f32 v13, v13, v14
	v_cvt_pk_bf16_f32 v14, v8, v9
	v_mul_f32_e32 v8, v10, v51
	v_mul_f32_e32 v9, v11, v51
	v_mul_f32_e32 v8, v8, v230
	v_mul_f32_e32 v9, v9, v231
	v_cvt_pk_bf16_f32 v15, v8, v9
	global_store_dwordx4 v[54:55], v[12:15], off offset:3072
	s_nop 0
	v_lshl_add_u32 v40, s2, 3, v40
	v_cmp_lt_i32_e32 vcc, s7, v40
	s_or_b64 s[4:5], vcc, s[4:5]
	s_andn2_b64 exec, exec, s[4:5]
	s_cbranch_execnz .LBB0_208

; DEVI int nblk() { int n = NBLK; asm volatile("" : "+s"(n)); return n; }
; DEVI int obid() { int b = blockIdx.x; asm volatile("" : "+s"(b)); return b; }
; DEVI int otid() { int t = threadIdx.x; asm volatile("" : "+v"(t)); return t; }
; DEVI void phase_rmsnorm(const float* __restrict__ x, const float* __restrict__ g, bfr* __restrict__ h, const float* __restrict__ xp = nullptr, const float* __restrict__ xs = nullptr) {
;   const int tid_ = otid(), wid = tid_ >> 6, lane = tid_ & 63;
;   for (int t = obid() * 8 + wid; t < T; t += nblk() * 8) {
;     const f32x4* xr = (const f32x4*)(xp ? (t < 16384 ? xp + (long)t * DM : xs + (long)(t - 16384) * DM) : x + (long)t * DM);
;     f32x4 v[8]; float ss = 0;
; #pragma unroll
;     for (int i = 0; i < 4; ++i) { v[2 * i] = xr[i * 128 + lane * 2]; v[2 * i + 1] = xr[i * 128 + lane * 2 + 1]; }
; #pragma unroll
;     for (int i = 0; i < 8; ++i) ss += v[i][0] * v[i][0] + v[i][1] * v[i][1] + v[i][2] * v[i][2] + v[i][3] * v[i][3];
;     ss = wave_sum(ss);
;     const float r = rsqrtf(ss * (1.f / DM) + EPS);
; #pragma unroll
;     for (int i = 0; i < 4; ++i) { const f32x4 g0 = ((const f32x4*)g)[i * 128 + lane * 2], g1 = ((const f32x4*)g)[i * 128 + lane * 2 + 1];
.LBB0_361:
	s_andn2_b64 vcc, exec, s[0:1]
	s_cbranch_vccnz .LBB0_367
	v_mov_b32_e32 v0, v164
	s_mov_b32 s0, s56
	s_nop 0
	v_ashrrev_i32_e32 v1, 6, v0
	v_lshl_add_u32 v40, s0, 3, v1
	s_mov_b32 s0, 0x8000
	v_cmp_gt_i32_e32 vcc, s0, v40
	s_and_saveexec_b64 s[0:1], vcc
	v_readlane_b32 s8, v255, 2
	v_readlane_b32 s10, v255, 4
	v_readlane_b32 s11, v255, 5
	s_mov_b32 s6, 0x800000
	s_movk_i32 s7, 0x7fff
	v_readlane_b32 s9, v255, 3
	s_cbranch_execz .LBB0_365
	v_readlane_b32 s4, v255, 21
	v_readlane_b32 s5, v255, 22
	s_lshl_b32 s4, s4, 11
	s_ashr_i32 s5, s4, 31
	s_lshl_b64 s[4:5], s[4:5], 2
	v_and_b32_e32 v8, 63, v0
	s_add_u32 s4, s44, s4
	v_lshlrev_b32_e32 v166, 4, v8
	s_addc_u32 s5, s45, s5
	v_lshl_add_u64 v[42:43], s[84:85], 0, v[166:167]
	v_lshlrev_b32_e32 v166, 5, v8
	global_load_dwordx4 v[0:3], v166, s[4:5]
	global_load_dwordx4 v[4:7], v166, s[4:5] offset:16
	v_and_b32_e32 v9, 64, v169
	v_add_u32_e32 v9, 64, v9
	v_xor_b32_e32 v10, 32, v169
	v_cmp_lt_i32_e32 vcc, v10, v9
	v_lshlrev_b32_e32 v8, 1, v8
	v_lshl_add_u64 v[44:45], s[4:5], 0, v[166:167]
	v_cndmask_b32_e32 v10, v169, v10, vcc
	v_lshlrev_b32_e32 v56, 2, v10
	v_xor_b32_e32 v10, 16, v169
	v_cmp_lt_i32_e32 vcc, v10, v9
	v_or_b32_e32 v12, 0x180, v8
	v_lshlrev_b32_e32 v52, 4, v12
	v_cndmask_b32_e32 v10, v169, v10, vcc
	v_lshlrev_b32_e32 v57, 2, v10
	v_xor_b32_e32 v10, 8, v169
	v_cmp_lt_i32_e32 vcc, v10, v9
	s_nop 1
	v_cndmask_b32_e32 v10, v169, v10, vcc
	v_lshlrev_b32_e32 v58, 2, v10
	v_xor_b32_e32 v10, 4, v169
	v_cmp_lt_i32_e32 vcc, v10, v9
	s_nop 1
	v_cndmask_b32_e32 v10, v169, v10, vcc
	v_lshlrev_b32_e32 v59, 2, v10
	v_xor_b32_e32 v10, 2, v169
	v_cmp_lt_i32_e32 vcc, v10, v9
	s_nop 1
	v_cndmask_b32_e32 v10, v169, v10, vcc
	v_lshlrev_b32_e32 v60, 2, v10
	v_xor_b32_e32 v10, 1, v169
	v_cmp_lt_i32_e32 vcc, v10, v9
	s_nop 1
	v_cndmask_b32_e32 v9, v169, v10, vcc
	v_or_b32_e32 v10, 0x100, v8
	v_lshlrev_b32_e32 v166, 4, v10
	v_lshl_add_u64 v[46:47], s[4:5], 0, v[166:167]
	v_lshlrev_b32_e32 v166, 4, v12
	v_lshlrev_b32_e32 v61, 2, v9
	v_lshl_add_u64 v[48:49], s[4:5], 0, v[166:167]
	s_mov_b64 s[4:5], 0
	v_lshlrev_b32_e32 v166, 4, v8
	v_lshlrev_b32_e32 v50, 4, v10
	global_load_dwordx4 v[208:211], v[44:45], off offset:2048
	global_load_dwordx4 v[212:215], v[44:45], off offset:2064
	global_load_dwordx4 v[216:219], v[46:47], off
	global_load_dwordx4 v[220:223], v[46:47], off offset:16
	global_load_dwordx4 v[224:227], v[48:49], off
	global_load_dwordx4 v[228:231], v[48:49], off offset:16

; DEVI int nblk() { int n = NBLK; asm volatile("" : "+s"(n)); return n; }
; DEVI int obid() { int b = blockIdx.x; asm volatile("" : "+s"(b)); return b; }
; DEVI int otid() { int t = threadIdx.x; asm volatile("" : "+v"(t)); return t; }
; DEVI void phase_rmsnorm(const float* __restrict__ x, const float* __restrict__ g, bfr* __restrict__ h, const float* __restrict__ xp = nullptr, const float* __restrict__ xs = nullptr) {
;   const int tid_ = otid(), wid = tid_ >> 6, lane = tid_ & 63;
;   for (int t = obid() * 8 + wid; t < T; t += nblk() * 8) {
;     const f32x4* xr = (const f32x4*)(xp ? (t < 16384 ? xp + (long)t * DM : xs + (long)(t - 16384) * DM) : x + (long)t * DM);
;     f32x4 v[8]; float ss = 0;
; #pragma unroll
;     for (int i = 0; i < 4; ++i) { v[2 * i] = xr[i * 128 + lane * 2]; v[2 * i + 1] = xr[i * 128 + lane * 2 + 1]; }
; #pragma unroll
;     for (int i = 0; i < 8; ++i) ss += v[i][0] * v[i][0] + v[i][1] * v[i][1] + v[i][2] * v[i][2] + v[i][3] * v[i][3];
;     ss = wave_sum(ss);
;     const float r = rsqrtf(ss * (1.f / DM) + EPS);
; #pragma unroll
;     for (int i = 0; i < 4; ++i) { const f32x4 g0 = ((const f32x4*)g)[i * 128 + lane * 2], g1 = ((const f32x4*)g)[i * 128 + lane * 2 + 1];
.LBB0_408:
	s_andn2_b64 vcc, exec, s[0:1]
	s_cbranch_vccnz .LBB0_413
	v_mov_b32_e32 v0, v164
	s_mov_b32 s0, s56
	s_nop 0
	v_ashrrev_i32_e32 v1, 6, v0
	v_lshl_add_u32 v40, s0, 3, v1
	s_mov_b32 s0, 0x8000
	v_cmp_gt_i32_e32 vcc, s0, v40
	s_and_saveexec_b64 s[0:1], vcc
	v_readlane_b32 s8, v255, 2
	v_readlane_b32 s10, v255, 4
	v_readlane_b32 s11, v255, 5
	s_mov_b32 s6, 0x800000
	s_movk_i32 s7, 0x7fff
	v_readlane_b32 s9, v255, 3
	s_cbranch_execz .LBB0_412
	s_lshl_b32 s4, s28, 11
	s_ashr_i32 s5, s4, 31
	s_lshl_b64 s[4:5], s[4:5], 2
	v_and_b32_e32 v8, 63, v0
	s_add_u32 s4, s48, s4
	v_lshlrev_b32_e32 v166, 4, v8
	s_addc_u32 s5, s49, s5
	v_lshl_add_u64 v[42:43], s[84:85], 0, v[166:167]
	v_lshlrev_b32_e32 v166, 5, v8
	global_load_dwordx4 v[0:3], v166, s[4:5]
	global_load_dwordx4 v[4:7], v166, s[4:5] offset:16
	v_and_b32_e32 v9, 64, v169
	v_add_u32_e32 v9, 64, v9
	v_xor_b32_e32 v10, 32, v169
	v_cmp_lt_i32_e32 vcc, v10, v9
	v_lshlrev_b32_e32 v8, 1, v8
	v_lshl_add_u64 v[44:45], s[4:5], 0, v[166:167]
	v_cndmask_b32_e32 v10, v169, v10, vcc
	v_lshlrev_b32_e32 v56, 2, v10
	v_xor_b32_e32 v10, 16, v169
	v_cmp_lt_i32_e32 vcc, v10, v9
	v_or_b32_e32 v12, 0x180, v8
	v_lshlrev_b32_e32 v52, 4, v12
	v_cndmask_b32_e32 v10, v169, v10, vcc
	v_lshlrev_b32_e32 v57, 2, v10
	v_xor_b32_e32 v10, 8, v169
	v_cmp_lt_i32_e32 vcc, v10, v9
	s_nop 1
	v_cndmask_b32_e32 v10, v169, v10, vcc
	v_lshlrev_b32_e32 v58, 2, v10
	v_xor_b32_e32 v10, 4, v169
	v_cmp_lt_i32_e32 vcc, v10, v9
	s_nop 1
	v_cndmask_b32_e32 v10, v169, v10, vcc
	v_lshlrev_b32_e32 v59, 2, v10
	v_xor_b32_e32 v10, 2, v169
	v_cmp_lt_i32_e32 vcc, v10, v9
	s_nop 1
	v_cndmask_b32_e32 v10, v169, v10, vcc
	v_lshlrev_b32_e32 v60, 2, v10
	v_xor_b32_e32 v10, 1, v169
	v_cmp_lt_i32_e32 vcc, v10, v9
	s_nop 1
	v_cndmask_b32_e32 v9, v169, v10, vcc
	v_or_b32_e32 v10, 0x100, v8
	v_lshlrev_b32_e32 v166, 4, v10
	v_lshl_add_u64 v[46:47], s[4:5], 0, v[166:167]
	v_lshlrev_b32_e32 v166, 4, v12
	v_lshlrev_b32_e32 v61, 2, v9
	v_lshl_add_u64 v[48:49], s[4:5], 0, v[166:167]
	s_mov_b64 s[4:5], 0
	v_lshlrev_b32_e32 v166, 4, v8
	v_lshlrev_b32_e32 v50, 4, v10
	global_load_dwordx4 v[208:211], v[44:45], off offset:2048
	global_load_dwordx4 v[212:215], v[44:45], off offset:2064
	global_load_dwordx4 v[216:219], v[46:47], off
	global_load_dwordx4 v[220:223], v[46:47], off offset:16
	global_load_dwordx4 v[224:227], v[48:49], off
	global_load_dwordx4 v[228:231], v[48:49], off offset:16

; template <bool COOP>
; __global__ __launch_bounds__(512, 2) void fwd_kernel(Params p) {
;   __shared__ __attribute__((aligned(1024))) char shm[2 * STAGE_B];
	.amdhsa_kernel _Z10fwd_kernelILb1EEv6Params
		.amdhsa_group_segment_fixed_size 131072
		.amdhsa_private_segment_fixed_size 0
		.amdhsa_kernarg_size 416
		.amdhsa_user_sgpr_count 2
		.amdhsa_user_sgpr_dispatch_ptr 0
		.amdhsa_user_sgpr_queue_ptr 0
		.amdhsa_user_sgpr_kernarg_segment_ptr 1
		.amdhsa_user_sgpr_dispatch_id 0
		.amdhsa_user_sgpr_kernarg_preload_length 0
		.amdhsa_user_sgpr_kernarg_preload_offset 0
		.amdhsa_user_sgpr_private_segment_size 0
		.amdhsa_uses_dynamic_stack 0
		.amdhsa_enable_private_segment 0
		.amdhsa_system_sgpr_workgroup_id_x 1
		.amdhsa_system_sgpr_workgroup_id_y 0
		.amdhsa_system_sgpr_workgroup_id_z 0
		.amdhsa_system_sgpr_workgroup_info 0
		.amdhsa_system_vgpr_workitem_id 2
		.amdhsa_next_free_vgpr 256
		.amdhsa_next_free_sgpr 102
		.amdhsa_accum_offset 256
		.amdhsa_reserve_vcc 1
		.amdhsa_float_round_mode_32 0
		.amdhsa_float_round_mode_16_64 0
		.amdhsa_float_denorm_mode_32 3
		.amdhsa_float_denorm_mode_16_64 3
		.amdhsa_dx10_clamp 1
		.amdhsa_ieee_mode 1
		.amdhsa_fp16_overflow 0
		.amdhsa_tg_split 0
		.amdhsa_exception_fp_ieee_invalid_op 0
		.amdhsa_exception_fp_denorm_src 0
		.amdhsa_exception_fp_ieee_div_zero 0
		.amdhsa_exception_fp_ieee_overflow 0
		.amdhsa_exception_fp_ieee_underflow 0
		.amdhsa_exception_fp_ieee_inexact 0
		.amdhsa_exception_int_div_zero 0
	.end_amdhsa_kernel

; template <bool COOP>
; __global__ __launch_bounds__(512, 2) void fwd_kernel(Params p) {
;   __shared__ __attribute__((aligned(1024))) char shm[2 * STAGE_B];
amdhsa.kernels:
  - .agpr_count:     0
    .args:
      - .offset:         0
        .size:           160
        .value_kind:     by_value
      - .offset:         160
        .size:           4
        .value_kind:     hidden_block_count_x
      - .offset:         164
        .size:           4
        .value_kind:     hidden_block_count_y
      - .offset:         168
        .size:           4
        .value_kind:     hidden_block_count_z
      - .offset:         172
        .size:           2
        .value_kind:     hidden_group_size_x
      - .offset:         174
        .size:           2
        .value_kind:     hidden_group_size_y
      - .offset:         176
        .size:           2
        .value_kind:     hidden_group_size_z
      - .offset:         178
        .size:           2
        .value_kind:     hidden_remainder_x
      - .offset:         180
        .size:           2
        .value_kind:     hidden_remainder_y
      - .offset:         182
        .size:           2
        .value_kind:     hidden_remainder_z
      - .offset:         200
        .size:           8
        .value_kind:     hidden_global_offset_x
      - .offset:         208
        .size:           8
        .value_kind:     hidden_global_offset_y
      - .offset:         216
        .size:           8
        .value_kind:     hidden_global_offset_z
      - .offset:         224
        .size:           2
        .value_kind:     hidden_grid_dims
      - .offset:         248
        .size:           8
        .value_kind:     hidden_multigrid_sync_arg
    .group_segment_fixed_size: 131072
    .kernarg_segment_align: 8
    .kernarg_segment_size: 416
    .language:       OpenCL C
    .language_version:
      - 2
      - 0
    .max_flat_workgroup_size: 512
    .name:           _Z10fwd_kernelILb1EEv6Params
    .private_segment_fixed_size: 0
    .sgpr_count:     108
    .sgpr_spill_count: 56
    .symbol:         _Z10fwd_kernelILb1EEv6Params.kd
    .uniform_work_group_size: 1
    .uses_dynamic_stack: false
    .vgpr_count:     256
    .vgpr_spill_count: 0
    .wavefront_size: 64
